# GEMM main loops without the per-segment s_setprio toggles (priority 0 throughout)
# speedup vs baseline: 1.0085x; 1.0085x over previous
.Lpeel_a:
	s_mov_b64 s[34:35], -1
	s_or_b32 s92, s89, 1
	s_lshl_b64 s[76:77], s[92:93], 7
	s_add_u32 s0, s10, s76
	s_addc_u32 s54, s11, s77
	s_add_i32 s92, s89, 2
	s_lshl_b64 s[78:79], s[92:93], 7
	s_add_u32 s80, s10, s78
	s_addc_u32 s81, s11, s79
	s_and_b64 s[76:77], s[34:35], exec
	s_cselect_b32 s77, s81, s57
	s_cselect_b32 s76, s80, s66
	s_add_u32 s78, s8, s78
	s_addc_u32 s79, s9, s79
	s_and_b64 s[34:35], s[34:35], exec
	s_cselect_b32 s35, s79, s63
	s_cselect_b32 s34, s78, s90
	s_add_i32 s80, 0, 0x10000
	s_add_i32 s81, 0, 0x14000
	v_add_u32_e32 v12, s80, v205
	v_add_u32_e32 v28, s81, v205
	ds_read_b128 v[0:3], v12
	ds_read_b128 v[4:7], v12 offset:1024
	ds_read_b128 v[8:11], v12 offset:2048
	ds_read_b128 v[12:15], v12 offset:3072
	ds_read_b128 v[16:19], v28
	ds_read_b128 v[20:23], v28 offset:1024
	ds_read_b128 v[24:27], v28 offset:2048
	ds_read_b128 v[28:31], v28 offset:3072
	s_add_u32 s78, s0, 0x40000
	s_addc_u32 s79, s54, 0
	v_lshl_add_u64 v[202:203], s[78:79], 0, v[184:185]
	s_add_i32 m0, s96, 0xc000
	ds_read_b128 v[166:169], v209
	ds_read_b128 v[170:173], v209 offset:1024
	ds_read_b128 v[174:177], v209 offset:2048
	ds_read_b128 v[178:181], v209 offset:3072
	ds_read_b128 v[196:199], v209 offset:4096
	ds_read_b128 v[210:213], v209 offset:5120
	ds_read_b128 v[244:247], v209 offset:6144
	ds_read_b128 v[248:251], v209 offset:7168
	global_load_lds_dwordx4 v[202:203], off
	v_lshl_add_u64 v[202:203], s[78:79], 0, v[186:187]
	s_add_i32 m0, s96, 0xe000
	s_nop 0
	global_load_lds_dwordx4 v[202:203], off
	s_waitcnt vmcnt(8)
	s_waitcnt lgkmcnt(0)
	s_barrier
	s_waitcnt lgkmcnt(0)
	v_mfma_f32_16x16x32_bf16 v[162:165], v[0:3], v[166:169], 0
	v_mfma_f32_16x16x32_bf16 v[158:161], v[8:11], v[166:169], 0
	v_mfma_f32_16x16x32_bf16 v[146:149], v[0:3], v[174:177], 0
	v_mfma_f32_16x16x32_bf16 v[142:145], v[8:11], v[174:177], 0
	v_mfma_f32_16x16x32_bf16 v[130:133], v[0:3], v[196:199], 0
	v_mfma_f32_16x16x32_bf16 v[126:129], v[8:11], v[196:199], 0
	v_mfma_f32_16x16x32_bf16 v[114:117], v[0:3], v[244:247], 0
	v_mfma_f32_16x16x32_bf16 v[110:113], v[8:11], v[244:247], 0
	v_mfma_f32_16x16x32_bf16 v[162:165], v[4:7], v[170:173], v[162:165]
	v_mfma_f32_16x16x32_bf16 v[158:161], v[12:15], v[170:173], v[158:161]
	v_mfma_f32_16x16x32_bf16 v[146:149], v[4:7], v[178:181], v[146:149]
	v_mfma_f32_16x16x32_bf16 v[142:145], v[12:15], v[178:181], v[142:145]
	v_mfma_f32_16x16x32_bf16 v[130:133], v[4:7], v[210:213], v[130:133]
	v_mfma_f32_16x16x32_bf16 v[126:129], v[12:15], v[210:213], v[126:129]
	v_mfma_f32_16x16x32_bf16 v[114:117], v[4:7], v[248:251], v[114:117]
	v_mfma_f32_16x16x32_bf16 v[110:113], v[12:15], v[248:251], v[110:113]
	v_mfma_f32_16x16x32_bf16 v[154:157], v[16:19], v[166:169], 0
	v_mfma_f32_16x16x32_bf16 v[150:153], v[24:27], v[166:169], 0
	v_mfma_f32_16x16x32_bf16 v[138:141], v[16:19], v[174:177], 0
	v_mfma_f32_16x16x32_bf16 v[134:137], v[24:27], v[174:177], 0
	v_mfma_f32_16x16x32_bf16 v[122:125], v[16:19], v[196:199], 0
	v_mfma_f32_16x16x32_bf16 v[118:121], v[24:27], v[196:199], 0
	v_mfma_f32_16x16x32_bf16 v[106:109], v[16:19], v[244:247], 0
	v_mfma_f32_16x16x32_bf16 v[102:105], v[24:27], v[244:247], 0
	v_mfma_f32_16x16x32_bf16 v[154:157], v[20:23], v[170:173], v[154:157]
	v_mfma_f32_16x16x32_bf16 v[150:153], v[28:31], v[170:173], v[150:153]
	v_mfma_f32_16x16x32_bf16 v[138:141], v[20:23], v[178:181], v[138:141]
	v_mfma_f32_16x16x32_bf16 v[134:137], v[28:31], v[178:181], v[134:137]
	v_mfma_f32_16x16x32_bf16 v[122:125], v[20:23], v[210:213], v[122:125]
	v_mfma_f32_16x16x32_bf16 v[118:121], v[28:31], v[210:213], v[118:121]
	v_mfma_f32_16x16x32_bf16 v[106:109], v[20:23], v[248:251], v[106:109]
	v_mfma_f32_16x16x32_bf16 v[102:105], v[28:31], v[248:251], v[102:105]
	s_barrier
	s_add_i32 s0, s80, s95
	v_lshl_add_u64 v[202:203], s[34:35], 0, v[182:183]
	s_mov_b32 m0, s0
	ds_read_b128 v[166:169], v209 offset:16384
	ds_read_b128 v[170:173], v209 offset:17408
	ds_read_b128 v[174:177], v209 offset:18432
	ds_read_b128 v[178:181], v209 offset:19456
	ds_read_b128 v[196:199], v209 offset:20480
	ds_read_b128 v[210:213], v209 offset:21504
	ds_read_b128 v[244:247], v209 offset:22528
	ds_read_b128 v[248:251], v209 offset:23552
	global_load_lds_dwordx4 v[202:203], off
	s_add_i32 m0, s0, 0x2000
	s_add_u32 s78, s34, 0x40000
	v_lshl_add_u64 v[214:215], s[34:35], 0, v[34:35]
	s_addc_u32 s79, s35, 0
	s_add_i32 s0, s81, s95
	global_load_lds_dwordx4 v[214:215], off
	v_lshl_add_u64 v[218:219], s[78:79], 0, v[182:183]
	s_mov_b32 m0, s0
	v_lshl_add_u64 v[222:223], s[76:77], 0, v[184:185]
	global_load_lds_dwordx4 v[218:219], off
	v_lshl_add_u64 v[218:219], s[78:79], 0, v[34:35]
	s_add_i32 m0, s0, 0x2000
	v_lshl_add_u64 v[236:237], s[76:77], 0, v[186:187]
	global_load_lds_dwordx4 v[218:219], off
	s_mov_b32 m0, s96
	s_nop 0
	global_load_lds_dwordx4 v[222:223], off
	s_mov_b32 m0, s97
	s_nop 0
	global_load_lds_dwordx4 v[236:237], off
	s_waitcnt vmcnt(8)
	s_waitcnt lgkmcnt(0)
	s_barrier
	s_waitcnt lgkmcnt(0)
	v_mfma_f32_16x16x32_bf16 v[98:101], v[0:3], v[166:169], 0
	v_mfma_f32_16x16x32_bf16 v[94:97], v[8:11], v[166:169], 0
	v_mfma_f32_16x16x32_bf16 v[82:85], v[0:3], v[174:177], 0
	v_mfma_f32_16x16x32_bf16 v[78:81], v[8:11], v[174:177], 0
	v_mfma_f32_16x16x32_bf16 v[66:69], v[0:3], v[196:199], 0
	v_mfma_f32_16x16x32_bf16 v[62:65], v[8:11], v[196:199], 0
	v_mfma_f32_16x16x32_bf16 v[0:3], v[0:3], v[244:247], 0
	v_mfma_f32_16x16x32_bf16 v[98:101], v[4:7], v[170:173], v[98:101]
	v_mfma_f32_16x16x32_bf16 v[94:97], v[12:15], v[170:173], v[94:97]
	v_mfma_f32_16x16x32_bf16 v[82:85], v[4:7], v[178:181], v[82:85]
	v_mfma_f32_16x16x32_bf16 v[78:81], v[12:15], v[178:181], v[78:81]
	v_mfma_f32_16x16x32_bf16 v[66:69], v[4:7], v[210:213], v[66:69]
	v_mfma_f32_16x16x32_bf16 v[62:65], v[12:15], v[210:213], v[62:65]
	v_mfma_f32_16x16x32_bf16 v[0:3], v[4:7], v[248:251], v[0:3]
	v_mfma_f32_16x16x32_bf16 v[4:7], v[8:11], v[244:247], 0
	v_mfma_f32_16x16x32_bf16 v[4:7], v[12:15], v[248:251], v[4:7]
	v_mfma_f32_16x16x32_bf16 v[46:49], v[16:19], v[174:177], 0
	v_mfma_f32_16x16x32_bf16 v[74:77], v[20:23], v[178:181], v[46:49]
	v_mfma_f32_16x16x32_bf16 v[46:49], v[24:27], v[174:177], 0
	v_mfma_f32_16x16x32_bf16 v[70:73], v[28:31], v[178:181], v[46:49]
	v_mfma_f32_16x16x32_bf16 v[46:49], v[16:19], v[196:199], 0
	v_mfma_f32_16x16x32_bf16 v[8:11], v[16:19], v[166:169], 0
	v_mfma_f32_16x16x32_bf16 v[58:61], v[20:23], v[210:213], v[46:49]
	v_mfma_f32_16x16x32_bf16 v[46:49], v[24:27], v[196:199], 0
	v_mfma_f32_16x16x32_bf16 v[16:19], v[16:19], v[244:247], 0
	v_mfma_f32_16x16x32_bf16 v[8:11], v[20:23], v[170:173], v[8:11]
	v_mfma_f32_16x16x32_bf16 v[12:15], v[24:27], v[166:169], 0
	v_mfma_f32_16x16x32_bf16 v[54:57], v[28:31], v[210:213], v[46:49]
	v_mfma_f32_16x16x32_bf16 v[16:19], v[20:23], v[248:251], v[16:19]
	v_mfma_f32_16x16x32_bf16 v[20:23], v[24:27], v[244:247], 0
	v_mfma_f32_16x16x32_bf16 v[12:15], v[28:31], v[170:173], v[12:15]
	v_mfma_f32_16x16x32_bf16 v[20:23], v[28:31], v[248:251], v[20:23]
	s_barrier
	s_add_i32 s0, 0, 0x18000
	v_add_u32_e32 v32, s0, v205
	s_add_i32 s54, 0, 0x1c000
	ds_read_b128 v[24:27], v32
	ds_read_b128 v[28:31], v32 offset:1024
	ds_read_b128 v[38:41], v32 offset:2048
	ds_read_b128 v[42:45], v32 offset:3072
	v_add_u32_e32 v32, s54, v205
	ds_read_b128 v[166:169], v32
	ds_read_b128 v[170:173], v32 offset:1024
	ds_read_b128 v[174:177], v32 offset:2048
	ds_read_b128 v[178:181], v32 offset:3072
	s_add_u32 s76, s76, 0x40000
	s_addc_u32 s77, s77, 0
	s_mov_b32 m0, s40
	v_lshl_add_u64 v[218:219], s[76:77], 0, v[184:185]
	ds_read_b128 v[46:49], v209 offset:32768
	ds_read_b128 v[50:53], v209 offset:33792
	ds_read_b128 v[86:89], v209 offset:34816
	ds_read_b128 v[90:93], v209 offset:35840
	ds_read_b128 v[196:199], v209 offset:36864
	ds_read_b128 v[210:213], v209 offset:37888
	ds_read_b128 v[244:247], v209 offset:38912
	ds_read_b128 v[248:251], v209 offset:39936
	global_load_lds_dwordx4 v[218:219], off
	v_lshl_add_u64 v[218:219], s[76:77], 0, v[186:187]
	s_mov_b32 m0, s41
	s_nop 0
	global_load_lds_dwordx4 v[218:219], off
	s_waitcnt vmcnt(8)
	s_waitcnt lgkmcnt(0)
	s_barrier
	s_waitcnt lgkmcnt(0)
	v_mfma_f32_16x16x32_bf16 v[162:165], v[24:27], v[46:49], v[162:165]
	v_mfma_f32_16x16x32_bf16 v[158:161], v[38:41], v[46:49], v[158:161]
	v_mfma_f32_16x16x32_bf16 v[146:149], v[24:27], v[86:89], v[146:149]
	v_mfma_f32_16x16x32_bf16 v[142:145], v[38:41], v[86:89], v[142:145]
	v_mfma_f32_16x16x32_bf16 v[130:133], v[24:27], v[196:199], v[130:133]
	v_mfma_f32_16x16x32_bf16 v[126:129], v[38:41], v[196:199], v[126:129]
	v_mfma_f32_16x16x32_bf16 v[114:117], v[24:27], v[244:247], v[114:117]
	v_mfma_f32_16x16x32_bf16 v[110:113], v[38:41], v[244:247], v[110:113]
	v_mfma_f32_16x16x32_bf16 v[162:165], v[28:31], v[50:53], v[162:165]
	v_mfma_f32_16x16x32_bf16 v[158:161], v[42:45], v[50:53], v[158:161]
	v_mfma_f32_16x16x32_bf16 v[146:149], v[28:31], v[90:93], v[146:149]
	v_mfma_f32_16x16x32_bf16 v[142:145], v[42:45], v[90:93], v[142:145]
	v_mfma_f32_16x16x32_bf16 v[130:133], v[28:31], v[210:213], v[130:133]
	v_mfma_f32_16x16x32_bf16 v[126:129], v[42:45], v[210:213], v[126:129]
	v_mfma_f32_16x16x32_bf16 v[114:117], v[28:31], v[248:251], v[114:117]
	v_mfma_f32_16x16x32_bf16 v[110:113], v[42:45], v[248:251], v[110:113]
	v_mfma_f32_16x16x32_bf16 v[154:157], v[166:169], v[46:49], v[154:157]
	v_mfma_f32_16x16x32_bf16 v[46:49], v[174:177], v[46:49], v[150:153]
	v_mfma_f32_16x16x32_bf16 v[150:153], v[178:181], v[50:53], v[46:49]
	v_mfma_f32_16x16x32_bf16 v[46:49], v[166:169], v[86:89], v[138:141]
	v_mfma_f32_16x16x32_bf16 v[138:141], v[170:173], v[90:93], v[46:49]
	v_mfma_f32_16x16x32_bf16 v[46:49], v[174:177], v[86:89], v[134:137]
	v_mfma_f32_16x16x32_bf16 v[134:137], v[178:181], v[90:93], v[46:49]
	v_mfma_f32_16x16x32_bf16 v[46:49], v[166:169], v[196:199], v[122:125]
	v_mfma_f32_16x16x32_bf16 v[122:125], v[170:173], v[210:213], v[46:49]
	v_mfma_f32_16x16x32_bf16 v[46:49], v[174:177], v[196:199], v[118:121]
	v_mfma_f32_16x16x32_bf16 v[118:121], v[178:181], v[210:213], v[46:49]
	v_mfma_f32_16x16x32_bf16 v[46:49], v[166:169], v[244:247], v[106:109]
	v_mfma_f32_16x16x32_bf16 v[106:109], v[170:173], v[248:251], v[46:49]
	v_mfma_f32_16x16x32_bf16 v[46:49], v[174:177], v[244:247], v[102:105]
	v_mfma_f32_16x16x32_bf16 v[154:157], v[170:173], v[50:53], v[154:157]
	v_mfma_f32_16x16x32_bf16 v[102:105], v[178:181], v[248:251], v[46:49]
	s_barrier
	s_add_i32 s0, s0, s95
	s_nop 2
	v_lshl_add_u64 v[46:47], v[202:203], 0, s[68:69]
	s_mov_b32 m0, s0
	ds_read_b128 v[86:89], v209 offset:49152
	ds_read_b128 v[196:199], v209 offset:50176
	ds_read_b128 v[210:213], v209 offset:51200
	ds_read_b128 v[244:247], v209 offset:52224
	ds_read_b128 v[248:251], v209 offset:53248
	ds_read_b128 v[228:231], v209 offset:54272
	ds_read_b128 v[232:235], v209 offset:55296
	ds_read_b128 v[218:221], v209 offset:56320
	global_load_lds_dwordx4 v[46:47], off
	s_add_i32 m0, s0, 0x2000
	s_add_u32 s34, s34, 0x40080
	v_lshl_add_u64 v[46:47], v[214:215], 0, s[68:69]
	s_addc_u32 s35, s35, 0
	s_add_i32 s0, s54, s95
	global_load_lds_dwordx4 v[46:47], off
	v_lshl_add_u64 v[46:47], s[34:35], 0, v[182:183]
	s_mov_b32 m0, s0
	s_nop 0
	global_load_lds_dwordx4 v[46:47], off
	v_lshl_add_u64 v[46:47], s[34:35], 0, v[34:35]
	s_add_i32 m0, s0, 0x2000
	s_nop 0
	global_load_lds_dwordx4 v[46:47], off
	v_lshl_add_u64 v[46:47], v[222:223], 0, s[68:69]
	s_mov_b32 m0, s43
	s_nop 0
	global_load_lds_dwordx4 v[46:47], off
	v_lshl_add_u64 v[46:47], v[236:237], 0, s[68:69]
	s_mov_b32 m0, s83
	s_nop 0
	global_load_lds_dwordx4 v[46:47], off
	s_waitcnt vmcnt(8)
	s_waitcnt lgkmcnt(0)
	s_barrier
	s_waitcnt lgkmcnt(0)
	v_mfma_f32_16x16x32_bf16 v[46:49], v[24:27], v[86:89], v[98:101]
	v_mfma_f32_16x16x32_bf16 v[98:101], v[28:31], v[196:199], v[46:49]
	v_mfma_f32_16x16x32_bf16 v[46:49], v[38:41], v[86:89], v[94:97]
	v_mfma_f32_16x16x32_bf16 v[94:97], v[42:45], v[196:199], v[46:49]
	v_mfma_f32_16x16x32_bf16 v[46:49], v[24:27], v[210:213], v[82:85]
	v_mfma_f32_16x16x32_bf16 v[82:85], v[28:31], v[244:247], v[46:49]
	v_mfma_f32_16x16x32_bf16 v[46:49], v[38:41], v[210:213], v[78:81]
	v_mfma_f32_16x16x32_bf16 v[78:81], v[42:45], v[244:247], v[46:49]
	v_mfma_f32_16x16x32_bf16 v[46:49], v[24:27], v[248:251], v[66:69]
	v_mfma_f32_16x16x32_bf16 v[0:3], v[24:27], v[232:235], v[0:3]
	v_mfma_f32_16x16x32_bf16 v[66:69], v[28:31], v[228:231], v[46:49]
	v_mfma_f32_16x16x32_bf16 v[46:49], v[38:41], v[248:251], v[62:65]
	v_mfma_f32_16x16x32_bf16 v[50:53], v[28:31], v[218:221], v[0:3]
	v_mfma_f32_16x16x32_bf16 v[0:3], v[38:41], v[232:235], v[4:7]
	v_mfma_f32_16x16x32_bf16 v[62:65], v[42:45], v[228:231], v[46:49]
	v_mfma_f32_16x16x32_bf16 v[46:49], v[42:45], v[218:221], v[0:3]
	v_mfma_f32_16x16x32_bf16 v[0:3], v[166:169], v[86:89], v[8:11]
	v_mfma_f32_16x16x32_bf16 v[90:93], v[170:173], v[196:199], v[0:3]
	v_mfma_f32_16x16x32_bf16 v[0:3], v[174:177], v[86:89], v[12:15]
	v_mfma_f32_16x16x32_bf16 v[86:89], v[178:181], v[196:199], v[0:3]
	v_mfma_f32_16x16x32_bf16 v[0:3], v[166:169], v[210:213], v[74:77]
	v_mfma_f32_16x16x32_bf16 v[74:77], v[170:173], v[244:247], v[0:3]
	v_mfma_f32_16x16x32_bf16 v[0:3], v[174:177], v[210:213], v[70:73]
	v_mfma_f32_16x16x32_bf16 v[70:73], v[178:181], v[244:247], v[0:3]
	v_mfma_f32_16x16x32_bf16 v[0:3], v[166:169], v[248:251], v[58:61]
	v_mfma_f32_16x16x32_bf16 v[58:61], v[170:173], v[228:231], v[0:3]
	v_mfma_f32_16x16x32_bf16 v[0:3], v[174:177], v[248:251], v[54:57]
	v_mfma_f32_16x16x32_bf16 v[54:57], v[178:181], v[228:231], v[0:3]
	v_mfma_f32_16x16x32_bf16 v[0:3], v[166:169], v[232:235], v[16:19]
	v_mfma_f32_16x16x32_bf16 v[42:45], v[170:173], v[218:221], v[0:3]
	v_mfma_f32_16x16x32_bf16 v[0:3], v[174:177], v[232:235], v[20:23]
	v_mfma_f32_16x16x32_bf16 v[38:41], v[178:181], v[218:221], v[0:3]
	s_barrier
	s_cmp_gt_u32 s89, 13
	s_mov_b32 s89, s92
	s_cbranch_scc1 .LBB0_343
	s_branch .LBB0_316
.LBB0_314:
.LBB0_315:
	s_or_b32 s92, s89, 1
	s_lshl_b64 s[76:77], s[92:93], 7
	s_add_u32 s0, s10, s76
	s_addc_u32 s54, s11, s77
	s_add_i32 s92, s89, 2
	s_lshl_b64 s[78:79], s[92:93], 7
	s_add_u32 s80, s10, s78
	s_addc_u32 s81, s11, s79
	s_and_b64 s[76:77], s[34:35], exec
	s_cselect_b32 s77, s81, s57
	s_cselect_b32 s76, s80, s66
	s_add_u32 s78, s8, s78
	s_addc_u32 s79, s9, s79
	s_and_b64 s[34:35], s[34:35], exec
	s_cselect_b32 s35, s79, s63
	s_cselect_b32 s34, s78, s90
	s_add_i32 s80, 0, 0x10000
	s_add_i32 s81, 0, 0x14000
	v_add_u32_e32 v12, s80, v205
	v_add_u32_e32 v28, s81, v205
	ds_read_b128 v[0:3], v12
	ds_read_b128 v[4:7], v12 offset:1024
	ds_read_b128 v[8:11], v12 offset:2048
	ds_read_b128 v[12:15], v12 offset:3072
	ds_read_b128 v[16:19], v28
	ds_read_b128 v[20:23], v28 offset:1024
	ds_read_b128 v[24:27], v28 offset:2048
	ds_read_b128 v[28:31], v28 offset:3072
	s_add_u32 s78, s0, 0x40000
	s_addc_u32 s79, s54, 0
	v_lshl_add_u64 v[202:203], s[78:79], 0, v[184:185]
	s_add_i32 m0, s96, 0xc000
	ds_read_b128 v[166:169], v209
	ds_read_b128 v[170:173], v209 offset:1024
	ds_read_b128 v[174:177], v209 offset:2048
	ds_read_b128 v[178:181], v209 offset:3072
	ds_read_b128 v[196:199], v209 offset:4096
	ds_read_b128 v[210:213], v209 offset:5120
	ds_read_b128 v[244:247], v209 offset:6144
	ds_read_b128 v[248:251], v209 offset:7168
	global_load_lds_dwordx4 v[202:203], off
	v_lshl_add_u64 v[202:203], s[78:79], 0, v[186:187]
	s_add_i32 m0, s96, 0xe000
	s_nop 0
	global_load_lds_dwordx4 v[202:203], off
	s_waitcnt vmcnt(8)
	s_waitcnt lgkmcnt(0)
	s_barrier
	s_waitcnt lgkmcnt(0)
	v_mfma_f32_16x16x32_bf16 v[162:165], v[0:3], v[166:169], v[162:165]
	v_mfma_f32_16x16x32_bf16 v[158:161], v[8:11], v[166:169], v[158:161]
	v_mfma_f32_16x16x32_bf16 v[146:149], v[0:3], v[174:177], v[146:149]
	v_mfma_f32_16x16x32_bf16 v[142:145], v[8:11], v[174:177], v[142:145]
	v_mfma_f32_16x16x32_bf16 v[130:133], v[0:3], v[196:199], v[130:133]
	v_mfma_f32_16x16x32_bf16 v[126:129], v[8:11], v[196:199], v[126:129]
	v_mfma_f32_16x16x32_bf16 v[114:117], v[0:3], v[244:247], v[114:117]
	v_mfma_f32_16x16x32_bf16 v[110:113], v[8:11], v[244:247], v[110:113]
	v_mfma_f32_16x16x32_bf16 v[162:165], v[4:7], v[170:173], v[162:165]
	v_mfma_f32_16x16x32_bf16 v[158:161], v[12:15], v[170:173], v[158:161]
	v_mfma_f32_16x16x32_bf16 v[146:149], v[4:7], v[178:181], v[146:149]
	v_mfma_f32_16x16x32_bf16 v[142:145], v[12:15], v[178:181], v[142:145]
	v_mfma_f32_16x16x32_bf16 v[130:133], v[4:7], v[210:213], v[130:133]
	v_mfma_f32_16x16x32_bf16 v[126:129], v[12:15], v[210:213], v[126:129]
	v_mfma_f32_16x16x32_bf16 v[114:117], v[4:7], v[248:251], v[114:117]
	v_mfma_f32_16x16x32_bf16 v[110:113], v[12:15], v[248:251], v[110:113]
	v_mfma_f32_16x16x32_bf16 v[154:157], v[16:19], v[166:169], v[154:157]
	v_mfma_f32_16x16x32_bf16 v[150:153], v[24:27], v[166:169], v[150:153]
	v_mfma_f32_16x16x32_bf16 v[138:141], v[16:19], v[174:177], v[138:141]
	v_mfma_f32_16x16x32_bf16 v[134:137], v[24:27], v[174:177], v[134:137]
	v_mfma_f32_16x16x32_bf16 v[122:125], v[16:19], v[196:199], v[122:125]
	v_mfma_f32_16x16x32_bf16 v[118:121], v[24:27], v[196:199], v[118:121]
	v_mfma_f32_16x16x32_bf16 v[106:109], v[16:19], v[244:247], v[106:109]
	v_mfma_f32_16x16x32_bf16 v[102:105], v[24:27], v[244:247], v[102:105]
	v_mfma_f32_16x16x32_bf16 v[154:157], v[20:23], v[170:173], v[154:157]
	v_mfma_f32_16x16x32_bf16 v[150:153], v[28:31], v[170:173], v[150:153]
	v_mfma_f32_16x16x32_bf16 v[138:141], v[20:23], v[178:181], v[138:141]
	v_mfma_f32_16x16x32_bf16 v[134:137], v[28:31], v[178:181], v[134:137]
	v_mfma_f32_16x16x32_bf16 v[122:125], v[20:23], v[210:213], v[122:125]
	v_mfma_f32_16x16x32_bf16 v[118:121], v[28:31], v[210:213], v[118:121]
	v_mfma_f32_16x16x32_bf16 v[106:109], v[20:23], v[248:251], v[106:109]
	v_mfma_f32_16x16x32_bf16 v[102:105], v[28:31], v[248:251], v[102:105]
	s_barrier
	s_add_i32 s0, s80, s95
	v_lshl_add_u64 v[202:203], s[34:35], 0, v[182:183]
	s_mov_b32 m0, s0
	ds_read_b128 v[166:169], v209 offset:16384
	ds_read_b128 v[170:173], v209 offset:17408
	ds_read_b128 v[174:177], v209 offset:18432
	ds_read_b128 v[178:181], v209 offset:19456
	ds_read_b128 v[196:199], v209 offset:20480
	ds_read_b128 v[210:213], v209 offset:21504
	ds_read_b128 v[244:247], v209 offset:22528
	ds_read_b128 v[248:251], v209 offset:23552
	global_load_lds_dwordx4 v[202:203], off
	s_add_i32 m0, s0, 0x2000
	s_add_u32 s78, s34, 0x40000
	v_lshl_add_u64 v[214:215], s[34:35], 0, v[34:35]
	s_addc_u32 s79, s35, 0
	s_add_i32 s0, s81, s95
	global_load_lds_dwordx4 v[214:215], off
	v_lshl_add_u64 v[218:219], s[78:79], 0, v[182:183]
	s_mov_b32 m0, s0
	v_lshl_add_u64 v[222:223], s[76:77], 0, v[184:185]
	global_load_lds_dwordx4 v[218:219], off
	v_lshl_add_u64 v[218:219], s[78:79], 0, v[34:35]
	s_add_i32 m0, s0, 0x2000
	v_lshl_add_u64 v[236:237], s[76:77], 0, v[186:187]
	global_load_lds_dwordx4 v[218:219], off
	s_mov_b32 m0, s96
	s_nop 0
	global_load_lds_dwordx4 v[222:223], off
	s_mov_b32 m0, s97
	s_nop 0
	global_load_lds_dwordx4 v[236:237], off
	s_waitcnt vmcnt(8)
	s_waitcnt lgkmcnt(0)
	s_barrier
	s_waitcnt lgkmcnt(0)
	v_mfma_f32_16x16x32_bf16 v[98:101], v[0:3], v[166:169], v[98:101]
	v_mfma_f32_16x16x32_bf16 v[94:97], v[8:11], v[166:169], v[94:97]
	v_mfma_f32_16x16x32_bf16 v[82:85], v[0:3], v[174:177], v[82:85]
	v_mfma_f32_16x16x32_bf16 v[78:81], v[8:11], v[174:177], v[78:81]
	v_mfma_f32_16x16x32_bf16 v[66:69], v[0:3], v[196:199], v[66:69]
	v_mfma_f32_16x16x32_bf16 v[62:65], v[8:11], v[196:199], v[62:65]
	v_mfma_f32_16x16x32_bf16 v[0:3], v[0:3], v[244:247], v[50:53]
	v_mfma_f32_16x16x32_bf16 v[98:101], v[4:7], v[170:173], v[98:101]
	v_mfma_f32_16x16x32_bf16 v[94:97], v[12:15], v[170:173], v[94:97]
	v_mfma_f32_16x16x32_bf16 v[82:85], v[4:7], v[178:181], v[82:85]
	v_mfma_f32_16x16x32_bf16 v[78:81], v[12:15], v[178:181], v[78:81]
	v_mfma_f32_16x16x32_bf16 v[66:69], v[4:7], v[210:213], v[66:69]
	v_mfma_f32_16x16x32_bf16 v[62:65], v[12:15], v[210:213], v[62:65]
	v_mfma_f32_16x16x32_bf16 v[0:3], v[4:7], v[248:251], v[0:3]
	v_mfma_f32_16x16x32_bf16 v[4:7], v[8:11], v[244:247], v[46:49]
	v_mfma_f32_16x16x32_bf16 v[4:7], v[12:15], v[248:251], v[4:7]
	v_mfma_f32_16x16x32_bf16 v[46:49], v[16:19], v[174:177], v[74:77]
	v_mfma_f32_16x16x32_bf16 v[74:77], v[20:23], v[178:181], v[46:49]
	v_mfma_f32_16x16x32_bf16 v[46:49], v[24:27], v[174:177], v[70:73]
	v_mfma_f32_16x16x32_bf16 v[70:73], v[28:31], v[178:181], v[46:49]
	v_mfma_f32_16x16x32_bf16 v[46:49], v[16:19], v[196:199], v[58:61]
	v_mfma_f32_16x16x32_bf16 v[8:11], v[16:19], v[166:169], v[90:93]
	v_mfma_f32_16x16x32_bf16 v[58:61], v[20:23], v[210:213], v[46:49]
	v_mfma_f32_16x16x32_bf16 v[46:49], v[24:27], v[196:199], v[54:57]
	v_mfma_f32_16x16x32_bf16 v[16:19], v[16:19], v[244:247], v[42:45]
	v_mfma_f32_16x16x32_bf16 v[8:11], v[20:23], v[170:173], v[8:11]
	v_mfma_f32_16x16x32_bf16 v[12:15], v[24:27], v[166:169], v[86:89]
	v_mfma_f32_16x16x32_bf16 v[54:57], v[28:31], v[210:213], v[46:49]
	v_mfma_f32_16x16x32_bf16 v[16:19], v[20:23], v[248:251], v[16:19]
	v_mfma_f32_16x16x32_bf16 v[20:23], v[24:27], v[244:247], v[38:41]
	v_mfma_f32_16x16x32_bf16 v[12:15], v[28:31], v[170:173], v[12:15]
	v_mfma_f32_16x16x32_bf16 v[20:23], v[28:31], v[248:251], v[20:23]
	s_barrier
	s_add_i32 s0, 0, 0x18000
	v_add_u32_e32 v32, s0, v205
	s_add_i32 s54, 0, 0x1c000
	ds_read_b128 v[24:27], v32
	ds_read_b128 v[28:31], v32 offset:1024
	ds_read_b128 v[38:41], v32 offset:2048
	ds_read_b128 v[42:45], v32 offset:3072
	v_add_u32_e32 v32, s54, v205
	ds_read_b128 v[166:169], v32
	ds_read_b128 v[170:173], v32 offset:1024
	ds_read_b128 v[174:177], v32 offset:2048
	ds_read_b128 v[178:181], v32 offset:3072
	s_add_u32 s76, s76, 0x40000
	s_addc_u32 s77, s77, 0
	s_mov_b32 m0, s40
	v_lshl_add_u64 v[218:219], s[76:77], 0, v[184:185]
	ds_read_b128 v[46:49], v209 offset:32768
	ds_read_b128 v[50:53], v209 offset:33792
	ds_read_b128 v[86:89], v209 offset:34816
	ds_read_b128 v[90:93], v209 offset:35840
	ds_read_b128 v[196:199], v209 offset:36864
	ds_read_b128 v[210:213], v209 offset:37888
	ds_read_b128 v[244:247], v209 offset:38912
	ds_read_b128 v[248:251], v209 offset:39936
	global_load_lds_dwordx4 v[218:219], off
	v_lshl_add_u64 v[218:219], s[76:77], 0, v[186:187]
	s_mov_b32 m0, s41
	s_nop 0
	global_load_lds_dwordx4 v[218:219], off
	s_waitcnt vmcnt(8)
	s_waitcnt lgkmcnt(0)
	s_barrier
	s_waitcnt lgkmcnt(0)
	v_mfma_f32_16x16x32_bf16 v[162:165], v[24:27], v[46:49], v[162:165]
	v_mfma_f32_16x16x32_bf16 v[158:161], v[38:41], v[46:49], v[158:161]
	v_mfma_f32_16x16x32_bf16 v[146:149], v[24:27], v[86:89], v[146:149]
	v_mfma_f32_16x16x32_bf16 v[142:145], v[38:41], v[86:89], v[142:145]
	v_mfma_f32_16x16x32_bf16 v[130:133], v[24:27], v[196:199], v[130:133]
	v_mfma_f32_16x16x32_bf16 v[126:129], v[38:41], v[196:199], v[126:129]
	v_mfma_f32_16x16x32_bf16 v[114:117], v[24:27], v[244:247], v[114:117]
	v_mfma_f32_16x16x32_bf16 v[110:113], v[38:41], v[244:247], v[110:113]
	v_mfma_f32_16x16x32_bf16 v[162:165], v[28:31], v[50:53], v[162:165]
	v_mfma_f32_16x16x32_bf16 v[158:161], v[42:45], v[50:53], v[158:161]
	v_mfma_f32_16x16x32_bf16 v[146:149], v[28:31], v[90:93], v[146:149]
	v_mfma_f32_16x16x32_bf16 v[142:145], v[42:45], v[90:93], v[142:145]
	v_mfma_f32_16x16x32_bf16 v[130:133], v[28:31], v[210:213], v[130:133]
	v_mfma_f32_16x16x32_bf16 v[126:129], v[42:45], v[210:213], v[126:129]
	v_mfma_f32_16x16x32_bf16 v[114:117], v[28:31], v[248:251], v[114:117]
	v_mfma_f32_16x16x32_bf16 v[110:113], v[42:45], v[248:251], v[110:113]
	v_mfma_f32_16x16x32_bf16 v[154:157], v[166:169], v[46:49], v[154:157]
	v_mfma_f32_16x16x32_bf16 v[46:49], v[174:177], v[46:49], v[150:153]
	v_mfma_f32_16x16x32_bf16 v[150:153], v[178:181], v[50:53], v[46:49]
	v_mfma_f32_16x16x32_bf16 v[46:49], v[166:169], v[86:89], v[138:141]
	v_mfma_f32_16x16x32_bf16 v[138:141], v[170:173], v[90:93], v[46:49]
	v_mfma_f32_16x16x32_bf16 v[46:49], v[174:177], v[86:89], v[134:137]
	v_mfma_f32_16x16x32_bf16 v[134:137], v[178:181], v[90:93], v[46:49]
	v_mfma_f32_16x16x32_bf16 v[46:49], v[166:169], v[196:199], v[122:125]
	v_mfma_f32_16x16x32_bf16 v[122:125], v[170:173], v[210:213], v[46:49]
	v_mfma_f32_16x16x32_bf16 v[46:49], v[174:177], v[196:199], v[118:121]
	v_mfma_f32_16x16x32_bf16 v[118:121], v[178:181], v[210:213], v[46:49]
	v_mfma_f32_16x16x32_bf16 v[46:49], v[166:169], v[244:247], v[106:109]
	v_mfma_f32_16x16x32_bf16 v[106:109], v[170:173], v[248:251], v[46:49]
	v_mfma_f32_16x16x32_bf16 v[46:49], v[174:177], v[244:247], v[102:105]
	v_mfma_f32_16x16x32_bf16 v[154:157], v[170:173], v[50:53], v[154:157]
	v_mfma_f32_16x16x32_bf16 v[102:105], v[178:181], v[248:251], v[46:49]
	s_barrier
	s_add_i32 s0, s0, s95
	s_nop 2
	v_lshl_add_u64 v[46:47], v[202:203], 0, s[68:69]
	s_mov_b32 m0, s0
	ds_read_b128 v[86:89], v209 offset:49152
	ds_read_b128 v[196:199], v209 offset:50176
	ds_read_b128 v[210:213], v209 offset:51200
	ds_read_b128 v[244:247], v209 offset:52224
	ds_read_b128 v[248:251], v209 offset:53248
	ds_read_b128 v[228:231], v209 offset:54272
	ds_read_b128 v[232:235], v209 offset:55296
	ds_read_b128 v[218:221], v209 offset:56320
	global_load_lds_dwordx4 v[46:47], off
	s_add_i32 m0, s0, 0x2000
	s_add_u32 s34, s34, 0x40080
	v_lshl_add_u64 v[46:47], v[214:215], 0, s[68:69]
	s_addc_u32 s35, s35, 0
	s_add_i32 s0, s54, s95
	global_load_lds_dwordx4 v[46:47], off
	v_lshl_add_u64 v[46:47], s[34:35], 0, v[182:183]
	s_mov_b32 m0, s0
	s_nop 0
	global_load_lds_dwordx4 v[46:47], off
	v_lshl_add_u64 v[46:47], s[34:35], 0, v[34:35]
	s_add_i32 m0, s0, 0x2000
	s_nop 0
	global_load_lds_dwordx4 v[46:47], off
	v_lshl_add_u64 v[46:47], v[222:223], 0, s[68:69]
	s_mov_b32 m0, s43
	s_nop 0
	global_load_lds_dwordx4 v[46:47], off
	v_lshl_add_u64 v[46:47], v[236:237], 0, s[68:69]
	s_mov_b32 m0, s83
	s_nop 0
	global_load_lds_dwordx4 v[46:47], off
	s_waitcnt vmcnt(8)
	s_waitcnt lgkmcnt(0)
	s_barrier
	s_waitcnt lgkmcnt(0)
	v_mfma_f32_16x16x32_bf16 v[46:49], v[24:27], v[86:89], v[98:101]
	v_mfma_f32_16x16x32_bf16 v[98:101], v[28:31], v[196:199], v[46:49]
	v_mfma_f32_16x16x32_bf16 v[46:49], v[38:41], v[86:89], v[94:97]
	v_mfma_f32_16x16x32_bf16 v[94:97], v[42:45], v[196:199], v[46:49]
	v_mfma_f32_16x16x32_bf16 v[46:49], v[24:27], v[210:213], v[82:85]
	v_mfma_f32_16x16x32_bf16 v[82:85], v[28:31], v[244:247], v[46:49]
	v_mfma_f32_16x16x32_bf16 v[46:49], v[38:41], v[210:213], v[78:81]
	v_mfma_f32_16x16x32_bf16 v[78:81], v[42:45], v[244:247], v[46:49]
	v_mfma_f32_16x16x32_bf16 v[46:49], v[24:27], v[248:251], v[66:69]
	v_mfma_f32_16x16x32_bf16 v[0:3], v[24:27], v[232:235], v[0:3]
	v_mfma_f32_16x16x32_bf16 v[66:69], v[28:31], v[228:231], v[46:49]
	v_mfma_f32_16x16x32_bf16 v[46:49], v[38:41], v[248:251], v[62:65]
	v_mfma_f32_16x16x32_bf16 v[50:53], v[28:31], v[218:221], v[0:3]
	v_mfma_f32_16x16x32_bf16 v[0:3], v[38:41], v[232:235], v[4:7]
	v_mfma_f32_16x16x32_bf16 v[62:65], v[42:45], v[228:231], v[46:49]
	v_mfma_f32_16x16x32_bf16 v[46:49], v[42:45], v[218:221], v[0:3]
	v_mfma_f32_16x16x32_bf16 v[0:3], v[166:169], v[86:89], v[8:11]
	v_mfma_f32_16x16x32_bf16 v[90:93], v[170:173], v[196:199], v[0:3]
	v_mfma_f32_16x16x32_bf16 v[0:3], v[174:177], v[86:89], v[12:15]
	v_mfma_f32_16x16x32_bf16 v[86:89], v[178:181], v[196:199], v[0:3]
	v_mfma_f32_16x16x32_bf16 v[0:3], v[166:169], v[210:213], v[74:77]
	v_mfma_f32_16x16x32_bf16 v[74:77], v[170:173], v[244:247], v[0:3]
	v_mfma_f32_16x16x32_bf16 v[0:3], v[174:177], v[210:213], v[70:73]
	v_mfma_f32_16x16x32_bf16 v[70:73], v[178:181], v[244:247], v[0:3]
	v_mfma_f32_16x16x32_bf16 v[0:3], v[166:169], v[248:251], v[58:61]
	v_mfma_f32_16x16x32_bf16 v[58:61], v[170:173], v[228:231], v[0:3]
	v_mfma_f32_16x16x32_bf16 v[0:3], v[174:177], v[248:251], v[54:57]
	v_mfma_f32_16x16x32_bf16 v[54:57], v[178:181], v[228:231], v[0:3]
	v_mfma_f32_16x16x32_bf16 v[0:3], v[166:169], v[232:235], v[16:19]
	v_mfma_f32_16x16x32_bf16 v[42:45], v[170:173], v[218:221], v[0:3]
	v_mfma_f32_16x16x32_bf16 v[0:3], v[174:177], v[232:235], v[20:23]
	v_mfma_f32_16x16x32_bf16 v[38:41], v[178:181], v[218:221], v[0:3]
	s_barrier
	s_cmp_gt_u32 s89, 13
	s_mov_b32 s89, s92
	s_cbranch_scc1 .LBB0_343

.Lpeel_b:
	s_mov_b64 s[34:35], -1
	s_or_b32 s92, s76, 1
	s_lshl_b64 s[42:43], s[92:93], 7
	s_add_u32 s0, s10, s42
	s_addc_u32 s48, s11, s43
	s_add_i32 s92, s76, 2
	s_lshl_b64 s[46:47], s[92:93], 7
	s_add_u32 s49, s10, s46
	s_addc_u32 s54, s11, s47
	s_and_b64 s[42:43], s[34:35], exec
	s_cselect_b32 s43, s54, s21
	s_cselect_b32 s42, s49, s66
	s_add_u32 s46, s8, s46
	s_addc_u32 s47, s9, s47
	s_and_b64 s[34:35], s[34:35], exec
	s_cselect_b32 s35, s47, s23
	s_cselect_b32 s34, s46, s74
	s_add_i32 s49, 0, 0x10000
	s_add_i32 s54, 0, 0x14000
	v_add_u32_e32 v12, s49, v205
	v_add_u32_e32 v28, s54, v205
	ds_read_b128 v[0:3], v12
	ds_read_b128 v[4:7], v12 offset:1024
	ds_read_b128 v[8:11], v12 offset:2048
	ds_read_b128 v[12:15], v12 offset:3072
	ds_read_b128 v[16:19], v28
	ds_read_b128 v[20:23], v28 offset:1024
	ds_read_b128 v[24:27], v28 offset:2048
	ds_read_b128 v[28:31], v28 offset:3072
	s_add_u32 s46, s0, 0x40000
	s_addc_u32 s47, s48, 0
	v_lshl_add_u64 v[202:203], s[46:47], 0, v[184:185]
	s_add_i32 m0, s53, 0xc000
	ds_read_b128 v[166:169], v209
	ds_read_b128 v[170:173], v209 offset:1024
	ds_read_b128 v[174:177], v209 offset:2048
	ds_read_b128 v[178:181], v209 offset:3072
	ds_read_b128 v[196:199], v209 offset:4096
	ds_read_b128 v[210:213], v209 offset:5120
	ds_read_b128 v[218:221], v209 offset:6144
	ds_read_b128 v[228:231], v209 offset:7168
	global_load_lds_dwordx4 v[202:203], off
	v_lshl_add_u64 v[202:203], s[46:47], 0, v[186:187]
	s_add_i32 m0, s53, 0xe000
	s_nop 0
	global_load_lds_dwordx4 v[202:203], off
	s_waitcnt vmcnt(8)
	s_waitcnt lgkmcnt(0)
	s_barrier
	s_waitcnt lgkmcnt(0)
	v_mfma_f32_16x16x32_bf16 v[162:165], v[0:3], v[166:169], 0
	v_mfma_f32_16x16x32_bf16 v[158:161], v[8:11], v[166:169], 0
	v_mfma_f32_16x16x32_bf16 v[146:149], v[0:3], v[174:177], 0
	v_mfma_f32_16x16x32_bf16 v[142:145], v[8:11], v[174:177], 0
	v_mfma_f32_16x16x32_bf16 v[130:133], v[0:3], v[196:199], 0
	v_mfma_f32_16x16x32_bf16 v[126:129], v[8:11], v[196:199], 0
	v_mfma_f32_16x16x32_bf16 v[114:117], v[0:3], v[218:221], 0
	v_mfma_f32_16x16x32_bf16 v[110:113], v[8:11], v[218:221], 0
	v_mfma_f32_16x16x32_bf16 v[162:165], v[4:7], v[170:173], v[162:165]
	v_mfma_f32_16x16x32_bf16 v[158:161], v[12:15], v[170:173], v[158:161]
	v_mfma_f32_16x16x32_bf16 v[146:149], v[4:7], v[178:181], v[146:149]
	v_mfma_f32_16x16x32_bf16 v[142:145], v[12:15], v[178:181], v[142:145]
	v_mfma_f32_16x16x32_bf16 v[130:133], v[4:7], v[210:213], v[130:133]
	v_mfma_f32_16x16x32_bf16 v[126:129], v[12:15], v[210:213], v[126:129]
	v_mfma_f32_16x16x32_bf16 v[114:117], v[4:7], v[228:231], v[114:117]
	v_mfma_f32_16x16x32_bf16 v[110:113], v[12:15], v[228:231], v[110:113]
	v_mfma_f32_16x16x32_bf16 v[154:157], v[16:19], v[166:169], 0
	v_mfma_f32_16x16x32_bf16 v[150:153], v[24:27], v[166:169], 0
	v_mfma_f32_16x16x32_bf16 v[138:141], v[16:19], v[174:177], 0
	v_mfma_f32_16x16x32_bf16 v[134:137], v[24:27], v[174:177], 0
	v_mfma_f32_16x16x32_bf16 v[122:125], v[16:19], v[196:199], 0
	v_mfma_f32_16x16x32_bf16 v[118:121], v[24:27], v[196:199], 0
	v_mfma_f32_16x16x32_bf16 v[106:109], v[16:19], v[218:221], 0
	v_mfma_f32_16x16x32_bf16 v[102:105], v[24:27], v[218:221], 0
	v_mfma_f32_16x16x32_bf16 v[154:157], v[20:23], v[170:173], v[154:157]
	v_mfma_f32_16x16x32_bf16 v[150:153], v[28:31], v[170:173], v[150:153]
	v_mfma_f32_16x16x32_bf16 v[138:141], v[20:23], v[178:181], v[138:141]
	v_mfma_f32_16x16x32_bf16 v[134:137], v[28:31], v[178:181], v[134:137]
	v_mfma_f32_16x16x32_bf16 v[122:125], v[20:23], v[210:213], v[122:125]
	v_mfma_f32_16x16x32_bf16 v[118:121], v[28:31], v[210:213], v[118:121]
	v_mfma_f32_16x16x32_bf16 v[106:109], v[20:23], v[228:231], v[106:109]
	v_mfma_f32_16x16x32_bf16 v[102:105], v[28:31], v[228:231], v[102:105]
	s_barrier
	s_add_i32 s0, s49, s52
	v_lshl_add_u64 v[202:203], s[34:35], 0, v[182:183]
	s_mov_b32 m0, s0
	ds_read_b128 v[166:169], v209 offset:16384
	ds_read_b128 v[170:173], v209 offset:17408
	ds_read_b128 v[174:177], v209 offset:18432
	ds_read_b128 v[178:181], v209 offset:19456
	ds_read_b128 v[196:199], v209 offset:20480
	ds_read_b128 v[210:213], v209 offset:21504
	ds_read_b128 v[218:221], v209 offset:22528
	ds_read_b128 v[228:231], v209 offset:23552
	global_load_lds_dwordx4 v[202:203], off
	s_add_i32 m0, s0, 0x2000
	s_add_u32 s46, s34, 0x40000
	v_lshl_add_u64 v[214:215], s[34:35], 0, v[34:35]
	s_addc_u32 s47, s35, 0
	s_add_i32 s0, s54, s52
	global_load_lds_dwordx4 v[214:215], off
	v_lshl_add_u64 v[222:223], s[46:47], 0, v[182:183]
	s_mov_b32 m0, s0
	v_lshl_add_u64 v[236:237], s[42:43], 0, v[186:187]
	global_load_lds_dwordx4 v[222:223], off
	v_lshl_add_u64 v[222:223], s[46:47], 0, v[34:35]
	s_add_i32 m0, s0, 0x2000
	s_nop 0
	global_load_lds_dwordx4 v[222:223], off
	v_lshl_add_u64 v[222:223], s[42:43], 0, v[184:185]
	s_mov_b32 m0, s53
	s_nop 0
	global_load_lds_dwordx4 v[222:223], off
	s_mov_b32 m0, s56
	s_nop 0
	global_load_lds_dwordx4 v[236:237], off
	s_waitcnt vmcnt(8)
	s_waitcnt lgkmcnt(0)
	s_barrier
	s_waitcnt lgkmcnt(0)
	v_mfma_f32_16x16x32_bf16 v[98:101], v[0:3], v[166:169], 0
	v_mfma_f32_16x16x32_bf16 v[94:97], v[8:11], v[166:169], 0
	v_mfma_f32_16x16x32_bf16 v[82:85], v[0:3], v[174:177], 0
	v_mfma_f32_16x16x32_bf16 v[78:81], v[8:11], v[174:177], 0
	v_mfma_f32_16x16x32_bf16 v[66:69], v[0:3], v[196:199], 0
	v_mfma_f32_16x16x32_bf16 v[62:65], v[8:11], v[196:199], 0
	v_mfma_f32_16x16x32_bf16 v[0:3], v[0:3], v[218:221], 0
	v_mfma_f32_16x16x32_bf16 v[98:101], v[4:7], v[170:173], v[98:101]
	v_mfma_f32_16x16x32_bf16 v[94:97], v[12:15], v[170:173], v[94:97]
	v_mfma_f32_16x16x32_bf16 v[82:85], v[4:7], v[178:181], v[82:85]
	v_mfma_f32_16x16x32_bf16 v[78:81], v[12:15], v[178:181], v[78:81]
	v_mfma_f32_16x16x32_bf16 v[66:69], v[4:7], v[210:213], v[66:69]
	v_mfma_f32_16x16x32_bf16 v[62:65], v[12:15], v[210:213], v[62:65]
	v_mfma_f32_16x16x32_bf16 v[0:3], v[4:7], v[228:231], v[0:3]
	v_mfma_f32_16x16x32_bf16 v[4:7], v[8:11], v[218:221], 0
	v_mfma_f32_16x16x32_bf16 v[4:7], v[12:15], v[228:231], v[4:7]
	v_mfma_f32_16x16x32_bf16 v[46:49], v[16:19], v[174:177], 0
	v_mfma_f32_16x16x32_bf16 v[74:77], v[20:23], v[178:181], v[46:49]
	v_mfma_f32_16x16x32_bf16 v[46:49], v[24:27], v[174:177], 0
	v_mfma_f32_16x16x32_bf16 v[70:73], v[28:31], v[178:181], v[46:49]
	v_mfma_f32_16x16x32_bf16 v[46:49], v[16:19], v[196:199], 0
	v_mfma_f32_16x16x32_bf16 v[8:11], v[16:19], v[166:169], 0
	v_mfma_f32_16x16x32_bf16 v[58:61], v[20:23], v[210:213], v[46:49]
	v_mfma_f32_16x16x32_bf16 v[46:49], v[24:27], v[196:199], 0
	v_mfma_f32_16x16x32_bf16 v[16:19], v[16:19], v[218:221], 0
	v_mfma_f32_16x16x32_bf16 v[8:11], v[20:23], v[170:173], v[8:11]
	v_mfma_f32_16x16x32_bf16 v[12:15], v[24:27], v[166:169], 0
	v_mfma_f32_16x16x32_bf16 v[54:57], v[28:31], v[210:213], v[46:49]
	v_mfma_f32_16x16x32_bf16 v[16:19], v[20:23], v[228:231], v[16:19]
	v_mfma_f32_16x16x32_bf16 v[20:23], v[24:27], v[218:221], 0
	v_mfma_f32_16x16x32_bf16 v[12:15], v[28:31], v[170:173], v[12:15]
	v_mfma_f32_16x16x32_bf16 v[20:23], v[28:31], v[228:231], v[20:23]
	s_barrier
	s_add_i32 s0, 0, 0x18000
	v_add_u32_e32 v32, s0, v205
	s_add_i32 s46, 0, 0x1c000
	ds_read_b128 v[24:27], v32
	ds_read_b128 v[28:31], v32 offset:1024
	ds_read_b128 v[38:41], v32 offset:2048
	ds_read_b128 v[42:45], v32 offset:3072
	v_add_u32_e32 v32, s46, v205
	ds_read_b128 v[166:169], v32
	ds_read_b128 v[170:173], v32 offset:1024
	ds_read_b128 v[174:177], v32 offset:2048
	ds_read_b128 v[178:181], v32 offset:3072
	s_add_u32 s42, s42, 0x40000
	s_addc_u32 s43, s43, 0
	s_mov_b32 m0, s57
	v_lshl_add_u64 v[232:233], s[42:43], 0, v[184:185]
	ds_read_b128 v[46:49], v209 offset:32768
	ds_read_b128 v[50:53], v209 offset:33792
	ds_read_b128 v[86:89], v209 offset:34816
	ds_read_b128 v[90:93], v209 offset:35840
	ds_read_b128 v[196:199], v209 offset:36864
	ds_read_b128 v[210:213], v209 offset:37888
	ds_read_b128 v[218:221], v209 offset:38912
	ds_read_b128 v[228:231], v209 offset:39936
	global_load_lds_dwordx4 v[232:233], off
	v_lshl_add_u64 v[232:233], s[42:43], 0, v[186:187]
	s_mov_b32 m0, s62
	s_nop 0
	global_load_lds_dwordx4 v[232:233], off
	s_waitcnt vmcnt(8)
	s_waitcnt lgkmcnt(0)
	s_barrier
	s_waitcnt lgkmcnt(0)
	v_mfma_f32_16x16x32_bf16 v[162:165], v[24:27], v[46:49], v[162:165]
	v_mfma_f32_16x16x32_bf16 v[158:161], v[38:41], v[46:49], v[158:161]
	v_mfma_f32_16x16x32_bf16 v[146:149], v[24:27], v[86:89], v[146:149]
	v_mfma_f32_16x16x32_bf16 v[142:145], v[38:41], v[86:89], v[142:145]
	v_mfma_f32_16x16x32_bf16 v[130:133], v[24:27], v[196:199], v[130:133]
	v_mfma_f32_16x16x32_bf16 v[126:129], v[38:41], v[196:199], v[126:129]
	v_mfma_f32_16x16x32_bf16 v[114:117], v[24:27], v[218:221], v[114:117]
	v_mfma_f32_16x16x32_bf16 v[110:113], v[38:41], v[218:221], v[110:113]
	v_mfma_f32_16x16x32_bf16 v[162:165], v[28:31], v[50:53], v[162:165]
	v_mfma_f32_16x16x32_bf16 v[158:161], v[42:45], v[50:53], v[158:161]
	v_mfma_f32_16x16x32_bf16 v[146:149], v[28:31], v[90:93], v[146:149]
	v_mfma_f32_16x16x32_bf16 v[142:145], v[42:45], v[90:93], v[142:145]
	v_mfma_f32_16x16x32_bf16 v[130:133], v[28:31], v[210:213], v[130:133]
	v_mfma_f32_16x16x32_bf16 v[126:129], v[42:45], v[210:213], v[126:129]
	v_mfma_f32_16x16x32_bf16 v[114:117], v[28:31], v[228:231], v[114:117]
	v_mfma_f32_16x16x32_bf16 v[110:113], v[42:45], v[228:231], v[110:113]
	v_mfma_f32_16x16x32_bf16 v[154:157], v[166:169], v[46:49], v[154:157]
	v_mfma_f32_16x16x32_bf16 v[46:49], v[174:177], v[46:49], v[150:153]
	v_mfma_f32_16x16x32_bf16 v[150:153], v[178:181], v[50:53], v[46:49]
	v_mfma_f32_16x16x32_bf16 v[46:49], v[166:169], v[86:89], v[138:141]
	v_mfma_f32_16x16x32_bf16 v[138:141], v[170:173], v[90:93], v[46:49]
	v_mfma_f32_16x16x32_bf16 v[46:49], v[174:177], v[86:89], v[134:137]
	v_mfma_f32_16x16x32_bf16 v[134:137], v[178:181], v[90:93], v[46:49]
	v_mfma_f32_16x16x32_bf16 v[46:49], v[166:169], v[196:199], v[122:125]
	v_mfma_f32_16x16x32_bf16 v[122:125], v[170:173], v[210:213], v[46:49]
	v_mfma_f32_16x16x32_bf16 v[46:49], v[174:177], v[196:199], v[118:121]
	v_mfma_f32_16x16x32_bf16 v[118:121], v[178:181], v[210:213], v[46:49]
	v_mfma_f32_16x16x32_bf16 v[46:49], v[166:169], v[218:221], v[106:109]
	v_mfma_f32_16x16x32_bf16 v[106:109], v[170:173], v[228:231], v[46:49]
	v_mfma_f32_16x16x32_bf16 v[46:49], v[174:177], v[218:221], v[102:105]
	v_mfma_f32_16x16x32_bf16 v[154:157], v[170:173], v[50:53], v[154:157]
	v_mfma_f32_16x16x32_bf16 v[102:105], v[178:181], v[228:231], v[46:49]
	s_barrier
	s_add_i32 s0, s0, s52
	s_nop 2
	v_lshl_add_u64 v[46:47], v[202:203], 0, s[68:69]
	s_mov_b32 m0, s0
	ds_read_b128 v[86:89], v209 offset:49152
	ds_read_b128 v[196:199], v209 offset:50176
	ds_read_b128 v[210:213], v209 offset:51200
	ds_read_b128 v[218:221], v209 offset:52224
	ds_read_b128 v[228:231], v209 offset:53248
	ds_read_b128 v[232:235], v209 offset:54272
	ds_read_b128 v[244:247], v209 offset:55296
	ds_read_b128 v[248:251], v209 offset:56320
	global_load_lds_dwordx4 v[46:47], off
	s_add_i32 m0, s0, 0x2000
	s_add_u32 s34, s34, 0x40080
	v_lshl_add_u64 v[46:47], v[214:215], 0, s[68:69]
	s_addc_u32 s35, s35, 0
	s_add_i32 s0, s46, s52
	global_load_lds_dwordx4 v[46:47], off
	v_lshl_add_u64 v[46:47], s[34:35], 0, v[182:183]
	s_mov_b32 m0, s0
	s_nop 0
	global_load_lds_dwordx4 v[46:47], off
	v_lshl_add_u64 v[46:47], s[34:35], 0, v[34:35]
	s_add_i32 m0, s0, 0x2000
	s_nop 0
	global_load_lds_dwordx4 v[46:47], off
	v_lshl_add_u64 v[46:47], v[222:223], 0, s[68:69]
	s_mov_b32 m0, s64
	s_nop 0
	global_load_lds_dwordx4 v[46:47], off
	v_lshl_add_u64 v[46:47], v[236:237], 0, s[68:69]
	s_mov_b32 m0, s65
	s_nop 0
	global_load_lds_dwordx4 v[46:47], off
	s_waitcnt vmcnt(8)
	s_waitcnt lgkmcnt(0)
	s_barrier
	s_waitcnt lgkmcnt(0)
	v_mfma_f32_16x16x32_bf16 v[46:49], v[24:27], v[86:89], v[98:101]
	v_mfma_f32_16x16x32_bf16 v[98:101], v[28:31], v[196:199], v[46:49]
	v_mfma_f32_16x16x32_bf16 v[46:49], v[38:41], v[86:89], v[94:97]
	v_mfma_f32_16x16x32_bf16 v[94:97], v[42:45], v[196:199], v[46:49]
	v_mfma_f32_16x16x32_bf16 v[46:49], v[24:27], v[210:213], v[82:85]
	v_mfma_f32_16x16x32_bf16 v[82:85], v[28:31], v[218:221], v[46:49]
	v_mfma_f32_16x16x32_bf16 v[46:49], v[38:41], v[210:213], v[78:81]
	v_mfma_f32_16x16x32_bf16 v[78:81], v[42:45], v[218:221], v[46:49]
	v_mfma_f32_16x16x32_bf16 v[46:49], v[24:27], v[228:231], v[66:69]
	v_mfma_f32_16x16x32_bf16 v[0:3], v[24:27], v[244:247], v[0:3]
	v_mfma_f32_16x16x32_bf16 v[66:69], v[28:31], v[232:235], v[46:49]
	v_mfma_f32_16x16x32_bf16 v[46:49], v[38:41], v[228:231], v[62:65]
	v_mfma_f32_16x16x32_bf16 v[50:53], v[28:31], v[248:251], v[0:3]
	v_mfma_f32_16x16x32_bf16 v[0:3], v[38:41], v[244:247], v[4:7]
	v_mfma_f32_16x16x32_bf16 v[62:65], v[42:45], v[232:235], v[46:49]
	v_mfma_f32_16x16x32_bf16 v[46:49], v[42:45], v[248:251], v[0:3]
	v_mfma_f32_16x16x32_bf16 v[0:3], v[166:169], v[86:89], v[8:11]
	v_mfma_f32_16x16x32_bf16 v[90:93], v[170:173], v[196:199], v[0:3]
	v_mfma_f32_16x16x32_bf16 v[0:3], v[174:177], v[86:89], v[12:15]
	v_mfma_f32_16x16x32_bf16 v[86:89], v[178:181], v[196:199], v[0:3]
	v_mfma_f32_16x16x32_bf16 v[0:3], v[166:169], v[210:213], v[74:77]
	v_mfma_f32_16x16x32_bf16 v[74:77], v[170:173], v[218:221], v[0:3]
	v_mfma_f32_16x16x32_bf16 v[0:3], v[174:177], v[210:213], v[70:73]
	v_mfma_f32_16x16x32_bf16 v[70:73], v[178:181], v[218:221], v[0:3]
	v_mfma_f32_16x16x32_bf16 v[0:3], v[166:169], v[228:231], v[58:61]
	v_mfma_f32_16x16x32_bf16 v[58:61], v[170:173], v[232:235], v[0:3]
	v_mfma_f32_16x16x32_bf16 v[0:3], v[174:177], v[228:231], v[54:57]
	v_mfma_f32_16x16x32_bf16 v[54:57], v[178:181], v[232:235], v[0:3]
	v_mfma_f32_16x16x32_bf16 v[0:3], v[166:169], v[244:247], v[16:19]
	v_mfma_f32_16x16x32_bf16 v[42:45], v[170:173], v[248:251], v[0:3]
	v_mfma_f32_16x16x32_bf16 v[0:3], v[174:177], v[244:247], v[20:23]
	v_mfma_f32_16x16x32_bf16 v[38:41], v[178:181], v[248:251], v[0:3]
	s_barrier
	s_cmp_gt_u32 s76, 13
	s_mov_b32 s76, s92
	s_cbranch_scc1 .LBB0_515
	s_branch .LBB0_483
.LBB0_481:
.LBB0_482:
	s_or_b32 s92, s76, 1
	s_lshl_b64 s[42:43], s[92:93], 7
	s_add_u32 s0, s10, s42
	s_addc_u32 s48, s11, s43
	s_add_i32 s92, s76, 2
	s_lshl_b64 s[46:47], s[92:93], 7
	s_add_u32 s49, s10, s46
	s_addc_u32 s54, s11, s47
	s_and_b64 s[42:43], s[34:35], exec
	s_cselect_b32 s43, s54, s21
	s_cselect_b32 s42, s49, s66
	s_add_u32 s46, s8, s46
	s_addc_u32 s47, s9, s47
	s_and_b64 s[34:35], s[34:35], exec
	s_cselect_b32 s35, s47, s23
	s_cselect_b32 s34, s46, s74
	s_add_i32 s49, 0, 0x10000
	s_add_i32 s54, 0, 0x14000
	v_add_u32_e32 v12, s49, v205
	v_add_u32_e32 v28, s54, v205
	ds_read_b128 v[0:3], v12
	ds_read_b128 v[4:7], v12 offset:1024
	ds_read_b128 v[8:11], v12 offset:2048
	ds_read_b128 v[12:15], v12 offset:3072
	ds_read_b128 v[16:19], v28
	ds_read_b128 v[20:23], v28 offset:1024
	ds_read_b128 v[24:27], v28 offset:2048
	ds_read_b128 v[28:31], v28 offset:3072
	s_add_u32 s46, s0, 0x40000
	s_addc_u32 s47, s48, 0
	v_lshl_add_u64 v[202:203], s[46:47], 0, v[184:185]
	s_add_i32 m0, s53, 0xc000
	ds_read_b128 v[166:169], v209
	ds_read_b128 v[170:173], v209 offset:1024
	ds_read_b128 v[174:177], v209 offset:2048
	ds_read_b128 v[178:181], v209 offset:3072
	ds_read_b128 v[196:199], v209 offset:4096
	ds_read_b128 v[210:213], v209 offset:5120
	ds_read_b128 v[218:221], v209 offset:6144
	ds_read_b128 v[228:231], v209 offset:7168
	global_load_lds_dwordx4 v[202:203], off
	v_lshl_add_u64 v[202:203], s[46:47], 0, v[186:187]
	s_add_i32 m0, s53, 0xe000
	s_nop 0
	global_load_lds_dwordx4 v[202:203], off
	s_waitcnt vmcnt(8)
	s_waitcnt lgkmcnt(0)
	s_barrier
	s_waitcnt lgkmcnt(0)
	v_mfma_f32_16x16x32_bf16 v[162:165], v[0:3], v[166:169], v[162:165]
	v_mfma_f32_16x16x32_bf16 v[158:161], v[8:11], v[166:169], v[158:161]
	v_mfma_f32_16x16x32_bf16 v[146:149], v[0:3], v[174:177], v[146:149]
	v_mfma_f32_16x16x32_bf16 v[142:145], v[8:11], v[174:177], v[142:145]
	v_mfma_f32_16x16x32_bf16 v[130:133], v[0:3], v[196:199], v[130:133]
	v_mfma_f32_16x16x32_bf16 v[126:129], v[8:11], v[196:199], v[126:129]
	v_mfma_f32_16x16x32_bf16 v[114:117], v[0:3], v[218:221], v[114:117]
	v_mfma_f32_16x16x32_bf16 v[110:113], v[8:11], v[218:221], v[110:113]
	v_mfma_f32_16x16x32_bf16 v[162:165], v[4:7], v[170:173], v[162:165]
	v_mfma_f32_16x16x32_bf16 v[158:161], v[12:15], v[170:173], v[158:161]
	v_mfma_f32_16x16x32_bf16 v[146:149], v[4:7], v[178:181], v[146:149]
	v_mfma_f32_16x16x32_bf16 v[142:145], v[12:15], v[178:181], v[142:145]
	v_mfma_f32_16x16x32_bf16 v[130:133], v[4:7], v[210:213], v[130:133]
	v_mfma_f32_16x16x32_bf16 v[126:129], v[12:15], v[210:213], v[126:129]
	v_mfma_f32_16x16x32_bf16 v[114:117], v[4:7], v[228:231], v[114:117]
	v_mfma_f32_16x16x32_bf16 v[110:113], v[12:15], v[228:231], v[110:113]
	v_mfma_f32_16x16x32_bf16 v[154:157], v[16:19], v[166:169], v[154:157]
	v_mfma_f32_16x16x32_bf16 v[150:153], v[24:27], v[166:169], v[150:153]
	v_mfma_f32_16x16x32_bf16 v[138:141], v[16:19], v[174:177], v[138:141]
	v_mfma_f32_16x16x32_bf16 v[134:137], v[24:27], v[174:177], v[134:137]
	v_mfma_f32_16x16x32_bf16 v[122:125], v[16:19], v[196:199], v[122:125]
	v_mfma_f32_16x16x32_bf16 v[118:121], v[24:27], v[196:199], v[118:121]
	v_mfma_f32_16x16x32_bf16 v[106:109], v[16:19], v[218:221], v[106:109]
	v_mfma_f32_16x16x32_bf16 v[102:105], v[24:27], v[218:221], v[102:105]
	v_mfma_f32_16x16x32_bf16 v[154:157], v[20:23], v[170:173], v[154:157]
	v_mfma_f32_16x16x32_bf16 v[150:153], v[28:31], v[170:173], v[150:153]
	v_mfma_f32_16x16x32_bf16 v[138:141], v[20:23], v[178:181], v[138:141]
	v_mfma_f32_16x16x32_bf16 v[134:137], v[28:31], v[178:181], v[134:137]
	v_mfma_f32_16x16x32_bf16 v[122:125], v[20:23], v[210:213], v[122:125]
	v_mfma_f32_16x16x32_bf16 v[118:121], v[28:31], v[210:213], v[118:121]
	v_mfma_f32_16x16x32_bf16 v[106:109], v[20:23], v[228:231], v[106:109]
	v_mfma_f32_16x16x32_bf16 v[102:105], v[28:31], v[228:231], v[102:105]
	s_barrier
	s_add_i32 s0, s49, s52
	v_lshl_add_u64 v[202:203], s[34:35], 0, v[182:183]
	s_mov_b32 m0, s0
	ds_read_b128 v[166:169], v209 offset:16384
	ds_read_b128 v[170:173], v209 offset:17408
	ds_read_b128 v[174:177], v209 offset:18432
	ds_read_b128 v[178:181], v209 offset:19456
	ds_read_b128 v[196:199], v209 offset:20480
	ds_read_b128 v[210:213], v209 offset:21504
	ds_read_b128 v[218:221], v209 offset:22528
	ds_read_b128 v[228:231], v209 offset:23552
	global_load_lds_dwordx4 v[202:203], off
	s_add_i32 m0, s0, 0x2000
	s_add_u32 s46, s34, 0x40000
	v_lshl_add_u64 v[214:215], s[34:35], 0, v[34:35]
	s_addc_u32 s47, s35, 0
	s_add_i32 s0, s54, s52
	global_load_lds_dwordx4 v[214:215], off
	v_lshl_add_u64 v[222:223], s[46:47], 0, v[182:183]
	s_mov_b32 m0, s0
	v_lshl_add_u64 v[236:237], s[42:43], 0, v[186:187]
	global_load_lds_dwordx4 v[222:223], off
	v_lshl_add_u64 v[222:223], s[46:47], 0, v[34:35]
	s_add_i32 m0, s0, 0x2000
	s_nop 0
	global_load_lds_dwordx4 v[222:223], off
	v_lshl_add_u64 v[222:223], s[42:43], 0, v[184:185]
	s_mov_b32 m0, s53
	s_nop 0
	global_load_lds_dwordx4 v[222:223], off
	s_mov_b32 m0, s56
	s_nop 0
	global_load_lds_dwordx4 v[236:237], off
	s_waitcnt vmcnt(8)
	s_waitcnt lgkmcnt(0)
	s_barrier
	s_waitcnt lgkmcnt(0)
	v_mfma_f32_16x16x32_bf16 v[98:101], v[0:3], v[166:169], v[98:101]
	v_mfma_f32_16x16x32_bf16 v[94:97], v[8:11], v[166:169], v[94:97]
	v_mfma_f32_16x16x32_bf16 v[82:85], v[0:3], v[174:177], v[82:85]
	v_mfma_f32_16x16x32_bf16 v[78:81], v[8:11], v[174:177], v[78:81]
	v_mfma_f32_16x16x32_bf16 v[66:69], v[0:3], v[196:199], v[66:69]
	v_mfma_f32_16x16x32_bf16 v[62:65], v[8:11], v[196:199], v[62:65]
	v_mfma_f32_16x16x32_bf16 v[0:3], v[0:3], v[218:221], v[50:53]
	v_mfma_f32_16x16x32_bf16 v[98:101], v[4:7], v[170:173], v[98:101]
	v_mfma_f32_16x16x32_bf16 v[94:97], v[12:15], v[170:173], v[94:97]
	v_mfma_f32_16x16x32_bf16 v[82:85], v[4:7], v[178:181], v[82:85]
	v_mfma_f32_16x16x32_bf16 v[78:81], v[12:15], v[178:181], v[78:81]
	v_mfma_f32_16x16x32_bf16 v[66:69], v[4:7], v[210:213], v[66:69]
	v_mfma_f32_16x16x32_bf16 v[62:65], v[12:15], v[210:213], v[62:65]
	v_mfma_f32_16x16x32_bf16 v[0:3], v[4:7], v[228:231], v[0:3]
	v_mfma_f32_16x16x32_bf16 v[4:7], v[8:11], v[218:221], v[46:49]
	v_mfma_f32_16x16x32_bf16 v[4:7], v[12:15], v[228:231], v[4:7]
	v_mfma_f32_16x16x32_bf16 v[46:49], v[16:19], v[174:177], v[74:77]
	v_mfma_f32_16x16x32_bf16 v[74:77], v[20:23], v[178:181], v[46:49]
	v_mfma_f32_16x16x32_bf16 v[46:49], v[24:27], v[174:177], v[70:73]
	v_mfma_f32_16x16x32_bf16 v[70:73], v[28:31], v[178:181], v[46:49]
	v_mfma_f32_16x16x32_bf16 v[46:49], v[16:19], v[196:199], v[58:61]
	v_mfma_f32_16x16x32_bf16 v[8:11], v[16:19], v[166:169], v[90:93]
	v_mfma_f32_16x16x32_bf16 v[58:61], v[20:23], v[210:213], v[46:49]
	v_mfma_f32_16x16x32_bf16 v[46:49], v[24:27], v[196:199], v[54:57]
	v_mfma_f32_16x16x32_bf16 v[16:19], v[16:19], v[218:221], v[42:45]
	v_mfma_f32_16x16x32_bf16 v[8:11], v[20:23], v[170:173], v[8:11]
	v_mfma_f32_16x16x32_bf16 v[12:15], v[24:27], v[166:169], v[86:89]
	v_mfma_f32_16x16x32_bf16 v[54:57], v[28:31], v[210:213], v[46:49]
	v_mfma_f32_16x16x32_bf16 v[16:19], v[20:23], v[228:231], v[16:19]
	v_mfma_f32_16x16x32_bf16 v[20:23], v[24:27], v[218:221], v[38:41]
	v_mfma_f32_16x16x32_bf16 v[12:15], v[28:31], v[170:173], v[12:15]
	v_mfma_f32_16x16x32_bf16 v[20:23], v[28:31], v[228:231], v[20:23]
	s_barrier
	s_add_i32 s0, 0, 0x18000
	v_add_u32_e32 v32, s0, v205
	s_add_i32 s46, 0, 0x1c000
	ds_read_b128 v[24:27], v32
	ds_read_b128 v[28:31], v32 offset:1024
	ds_read_b128 v[38:41], v32 offset:2048
	ds_read_b128 v[42:45], v32 offset:3072
	v_add_u32_e32 v32, s46, v205
	ds_read_b128 v[166:169], v32
	ds_read_b128 v[170:173], v32 offset:1024
	ds_read_b128 v[174:177], v32 offset:2048
	ds_read_b128 v[178:181], v32 offset:3072
	s_add_u32 s42, s42, 0x40000
	s_addc_u32 s43, s43, 0
	s_mov_b32 m0, s57
	v_lshl_add_u64 v[232:233], s[42:43], 0, v[184:185]
	ds_read_b128 v[46:49], v209 offset:32768
	ds_read_b128 v[50:53], v209 offset:33792
	ds_read_b128 v[86:89], v209 offset:34816
	ds_read_b128 v[90:93], v209 offset:35840
	ds_read_b128 v[196:199], v209 offset:36864
	ds_read_b128 v[210:213], v209 offset:37888
	ds_read_b128 v[218:221], v209 offset:38912
	ds_read_b128 v[228:231], v209 offset:39936
	global_load_lds_dwordx4 v[232:233], off
	v_lshl_add_u64 v[232:233], s[42:43], 0, v[186:187]
	s_mov_b32 m0, s62
	s_nop 0
	global_load_lds_dwordx4 v[232:233], off
	s_waitcnt vmcnt(8)
	s_waitcnt lgkmcnt(0)
	s_barrier
	s_waitcnt lgkmcnt(0)
	v_mfma_f32_16x16x32_bf16 v[162:165], v[24:27], v[46:49], v[162:165]
	v_mfma_f32_16x16x32_bf16 v[158:161], v[38:41], v[46:49], v[158:161]
	v_mfma_f32_16x16x32_bf16 v[146:149], v[24:27], v[86:89], v[146:149]
	v_mfma_f32_16x16x32_bf16 v[142:145], v[38:41], v[86:89], v[142:145]
	v_mfma_f32_16x16x32_bf16 v[130:133], v[24:27], v[196:199], v[130:133]
	v_mfma_f32_16x16x32_bf16 v[126:129], v[38:41], v[196:199], v[126:129]
	v_mfma_f32_16x16x32_bf16 v[114:117], v[24:27], v[218:221], v[114:117]
	v_mfma_f32_16x16x32_bf16 v[110:113], v[38:41], v[218:221], v[110:113]
	v_mfma_f32_16x16x32_bf16 v[162:165], v[28:31], v[50:53], v[162:165]
	v_mfma_f32_16x16x32_bf16 v[158:161], v[42:45], v[50:53], v[158:161]
	v_mfma_f32_16x16x32_bf16 v[146:149], v[28:31], v[90:93], v[146:149]
	v_mfma_f32_16x16x32_bf16 v[142:145], v[42:45], v[90:93], v[142:145]
	v_mfma_f32_16x16x32_bf16 v[130:133], v[28:31], v[210:213], v[130:133]
	v_mfma_f32_16x16x32_bf16 v[126:129], v[42:45], v[210:213], v[126:129]
	v_mfma_f32_16x16x32_bf16 v[114:117], v[28:31], v[228:231], v[114:117]
	v_mfma_f32_16x16x32_bf16 v[110:113], v[42:45], v[228:231], v[110:113]
	v_mfma_f32_16x16x32_bf16 v[154:157], v[166:169], v[46:49], v[154:157]
	v_mfma_f32_16x16x32_bf16 v[46:49], v[174:177], v[46:49], v[150:153]
	v_mfma_f32_16x16x32_bf16 v[150:153], v[178:181], v[50:53], v[46:49]
	v_mfma_f32_16x16x32_bf16 v[46:49], v[166:169], v[86:89], v[138:141]
	v_mfma_f32_16x16x32_bf16 v[138:141], v[170:173], v[90:93], v[46:49]
	v_mfma_f32_16x16x32_bf16 v[46:49], v[174:177], v[86:89], v[134:137]
	v_mfma_f32_16x16x32_bf16 v[134:137], v[178:181], v[90:93], v[46:49]
	v_mfma_f32_16x16x32_bf16 v[46:49], v[166:169], v[196:199], v[122:125]
	v_mfma_f32_16x16x32_bf16 v[122:125], v[170:173], v[210:213], v[46:49]
	v_mfma_f32_16x16x32_bf16 v[46:49], v[174:177], v[196:199], v[118:121]
	v_mfma_f32_16x16x32_bf16 v[118:121], v[178:181], v[210:213], v[46:49]
	v_mfma_f32_16x16x32_bf16 v[46:49], v[166:169], v[218:221], v[106:109]
	v_mfma_f32_16x16x32_bf16 v[106:109], v[170:173], v[228:231], v[46:49]
	v_mfma_f32_16x16x32_bf16 v[46:49], v[174:177], v[218:221], v[102:105]
	v_mfma_f32_16x16x32_bf16 v[154:157], v[170:173], v[50:53], v[154:157]
	v_mfma_f32_16x16x32_bf16 v[102:105], v[178:181], v[228:231], v[46:49]
	s_barrier
	s_add_i32 s0, s0, s52
	s_nop 2
	v_lshl_add_u64 v[46:47], v[202:203], 0, s[68:69]
	s_mov_b32 m0, s0
	ds_read_b128 v[86:89], v209 offset:49152
	ds_read_b128 v[196:199], v209 offset:50176
	ds_read_b128 v[210:213], v209 offset:51200
	ds_read_b128 v[218:221], v209 offset:52224
	ds_read_b128 v[228:231], v209 offset:53248
	ds_read_b128 v[232:235], v209 offset:54272
	ds_read_b128 v[244:247], v209 offset:55296
	ds_read_b128 v[248:251], v209 offset:56320
	global_load_lds_dwordx4 v[46:47], off
	s_add_i32 m0, s0, 0x2000
	s_add_u32 s34, s34, 0x40080
	v_lshl_add_u64 v[46:47], v[214:215], 0, s[68:69]
	s_addc_u32 s35, s35, 0
	s_add_i32 s0, s46, s52
	global_load_lds_dwordx4 v[46:47], off
	v_lshl_add_u64 v[46:47], s[34:35], 0, v[182:183]
	s_mov_b32 m0, s0
	s_nop 0
	global_load_lds_dwordx4 v[46:47], off
	v_lshl_add_u64 v[46:47], s[34:35], 0, v[34:35]
	s_add_i32 m0, s0, 0x2000
	s_nop 0
	global_load_lds_dwordx4 v[46:47], off
	v_lshl_add_u64 v[46:47], v[222:223], 0, s[68:69]
	s_mov_b32 m0, s64
	s_nop 0
	global_load_lds_dwordx4 v[46:47], off
	v_lshl_add_u64 v[46:47], v[236:237], 0, s[68:69]
	s_mov_b32 m0, s65
	s_nop 0
	global_load_lds_dwordx4 v[46:47], off
	s_waitcnt vmcnt(8)
	s_waitcnt lgkmcnt(0)
	s_barrier
	s_waitcnt lgkmcnt(0)
	v_mfma_f32_16x16x32_bf16 v[46:49], v[24:27], v[86:89], v[98:101]
	v_mfma_f32_16x16x32_bf16 v[98:101], v[28:31], v[196:199], v[46:49]
	v_mfma_f32_16x16x32_bf16 v[46:49], v[38:41], v[86:89], v[94:97]
	v_mfma_f32_16x16x32_bf16 v[94:97], v[42:45], v[196:199], v[46:49]
	v_mfma_f32_16x16x32_bf16 v[46:49], v[24:27], v[210:213], v[82:85]
	v_mfma_f32_16x16x32_bf16 v[82:85], v[28:31], v[218:221], v[46:49]
	v_mfma_f32_16x16x32_bf16 v[46:49], v[38:41], v[210:213], v[78:81]
	v_mfma_f32_16x16x32_bf16 v[78:81], v[42:45], v[218:221], v[46:49]
	v_mfma_f32_16x16x32_bf16 v[46:49], v[24:27], v[228:231], v[66:69]
	v_mfma_f32_16x16x32_bf16 v[0:3], v[24:27], v[244:247], v[0:3]
	v_mfma_f32_16x16x32_bf16 v[66:69], v[28:31], v[232:235], v[46:49]
	v_mfma_f32_16x16x32_bf16 v[46:49], v[38:41], v[228:231], v[62:65]
	v_mfma_f32_16x16x32_bf16 v[50:53], v[28:31], v[248:251], v[0:3]
	v_mfma_f32_16x16x32_bf16 v[0:3], v[38:41], v[244:247], v[4:7]
	v_mfma_f32_16x16x32_bf16 v[62:65], v[42:45], v[232:235], v[46:49]
	v_mfma_f32_16x16x32_bf16 v[46:49], v[42:45], v[248:251], v[0:3]
	v_mfma_f32_16x16x32_bf16 v[0:3], v[166:169], v[86:89], v[8:11]
	v_mfma_f32_16x16x32_bf16 v[90:93], v[170:173], v[196:199], v[0:3]
	v_mfma_f32_16x16x32_bf16 v[0:3], v[174:177], v[86:89], v[12:15]
	v_mfma_f32_16x16x32_bf16 v[86:89], v[178:181], v[196:199], v[0:3]
	v_mfma_f32_16x16x32_bf16 v[0:3], v[166:169], v[210:213], v[74:77]
	v_mfma_f32_16x16x32_bf16 v[74:77], v[170:173], v[218:221], v[0:3]
	v_mfma_f32_16x16x32_bf16 v[0:3], v[174:177], v[210:213], v[70:73]
	v_mfma_f32_16x16x32_bf16 v[70:73], v[178:181], v[218:221], v[0:3]
	v_mfma_f32_16x16x32_bf16 v[0:3], v[166:169], v[228:231], v[58:61]
	v_mfma_f32_16x16x32_bf16 v[58:61], v[170:173], v[232:235], v[0:3]
	v_mfma_f32_16x16x32_bf16 v[0:3], v[174:177], v[228:231], v[54:57]
	v_mfma_f32_16x16x32_bf16 v[54:57], v[178:181], v[232:235], v[0:3]
	v_mfma_f32_16x16x32_bf16 v[0:3], v[166:169], v[244:247], v[16:19]
	v_mfma_f32_16x16x32_bf16 v[42:45], v[170:173], v[248:251], v[0:3]
	v_mfma_f32_16x16x32_bf16 v[0:3], v[174:177], v[244:247], v[20:23]
	v_mfma_f32_16x16x32_bf16 v[38:41], v[178:181], v[248:251], v[0:3]
	s_barrier
	s_cmp_gt_u32 s76, 13
	s_mov_b32 s76, s92
	s_cbranch_scc1 .LBB0_515

.LBB0_899:
	s_add_i32 s74, s34, 2
	s_add_u32 s12, s10, 0x100
	s_addc_u32 s13, s11, 0
	s_add_i32 s75, 0, 0x10000
	s_cmp_eq_u32 s0, s34
	s_cselect_b32 s39, s31, s13
	s_cselect_b32 s38, s30, s12
	s_cselect_b32 s35, s37, s54
	s_cselect_b32 s34, s36, s29
	s_add_i32 s76, 0, 0x14000
	v_add_u32_e32 v146, s75, v201
	v_add_u32_e32 v162, s76, v201
	ds_read_b128 v[134:137], v146
	ds_read_b128 v[138:141], v146 offset:1024
	ds_read_b128 v[142:145], v146 offset:2048
	ds_read_b128 v[146:149], v146 offset:3072
	ds_read_b128 v[150:153], v162
	ds_read_b128 v[154:157], v162 offset:1024
	ds_read_b128 v[158:161], v162 offset:2048
	ds_read_b128 v[162:165], v162 offset:3072
	v_lshl_add_u64 v[210:211], s[10:11], 0, v[206:207]
	s_add_i32 m0, s46, 0xc000
	ds_read_b128 v[166:169], v244
	ds_read_b128 v[170:173], v244 offset:1024
	ds_read_b128 v[174:177], v244 offset:2048
	ds_read_b128 v[178:181], v244 offset:3072
	ds_read_b128 v[182:185], v244 offset:4096
	ds_read_b128 v[186:189], v244 offset:5120
	ds_read_b128 v[190:193], v244 offset:6144
	ds_read_b128 v[194:197], v244 offset:7168
	global_load_lds_dwordx4 v[210:211], off
	v_lshl_add_u64 v[210:211], s[10:11], 0, v[208:209]
	s_add_i32 m0, s46, 0xe000
	s_nop 0
	global_load_lds_dwordx4 v[210:211], off
	s_waitcnt vmcnt(8)
	s_waitcnt lgkmcnt(0)
	s_barrier
	s_waitcnt lgkmcnt(0)
	v_mfma_f32_16x16x32_bf16 v[130:133], v[134:137], v[166:169], v[130:133]
	v_mfma_f32_16x16x32_bf16 v[126:129], v[142:145], v[166:169], v[126:129]
	v_mfma_f32_16x16x32_bf16 v[122:125], v[134:137], v[174:177], v[122:125]
	v_mfma_f32_16x16x32_bf16 v[118:121], v[142:145], v[174:177], v[118:121]
	v_mfma_f32_16x16x32_bf16 v[114:117], v[134:137], v[182:185], v[114:117]
	v_mfma_f32_16x16x32_bf16 v[110:113], v[142:145], v[182:185], v[110:113]
	v_mfma_f32_16x16x32_bf16 v[106:109], v[134:137], v[190:193], v[106:109]
	v_mfma_f32_16x16x32_bf16 v[102:105], v[142:145], v[190:193], v[102:105]
	v_mfma_f32_16x16x32_bf16 v[130:133], v[138:141], v[170:173], v[130:133]
	v_mfma_f32_16x16x32_bf16 v[126:129], v[146:149], v[170:173], v[126:129]
	v_mfma_f32_16x16x32_bf16 v[122:125], v[138:141], v[178:181], v[122:125]
	v_mfma_f32_16x16x32_bf16 v[118:121], v[146:149], v[178:181], v[118:121]
	v_mfma_f32_16x16x32_bf16 v[114:117], v[138:141], v[186:189], v[114:117]
	v_mfma_f32_16x16x32_bf16 v[110:113], v[146:149], v[186:189], v[110:113]
	v_mfma_f32_16x16x32_bf16 v[106:109], v[138:141], v[194:197], v[106:109]
	v_mfma_f32_16x16x32_bf16 v[102:105], v[146:149], v[194:197], v[102:105]
	v_mfma_f32_16x16x32_bf16 v[98:101], v[150:153], v[166:169], v[98:101]
	v_mfma_f32_16x16x32_bf16 v[94:97], v[158:161], v[166:169], v[94:97]
	v_mfma_f32_16x16x32_bf16 v[90:93], v[150:153], v[174:177], v[90:93]
	v_mfma_f32_16x16x32_bf16 v[86:89], v[158:161], v[174:177], v[86:89]
	v_mfma_f32_16x16x32_bf16 v[82:85], v[150:153], v[182:185], v[82:85]
	v_mfma_f32_16x16x32_bf16 v[78:81], v[158:161], v[182:185], v[78:81]
	v_mfma_f32_16x16x32_bf16 v[74:77], v[150:153], v[190:193], v[74:77]
	v_mfma_f32_16x16x32_bf16 v[70:73], v[158:161], v[190:193], v[70:73]
	v_mfma_f32_16x16x32_bf16 v[98:101], v[154:157], v[170:173], v[98:101]
	v_mfma_f32_16x16x32_bf16 v[94:97], v[162:165], v[170:173], v[94:97]
	v_mfma_f32_16x16x32_bf16 v[90:93], v[154:157], v[178:181], v[90:93]
	v_mfma_f32_16x16x32_bf16 v[86:89], v[162:165], v[178:181], v[86:89]
	v_mfma_f32_16x16x32_bf16 v[82:85], v[154:157], v[186:189], v[82:85]
	v_mfma_f32_16x16x32_bf16 v[78:81], v[162:165], v[186:189], v[78:81]
	v_mfma_f32_16x16x32_bf16 v[74:77], v[154:157], v[194:197], v[74:77]
	v_mfma_f32_16x16x32_bf16 v[70:73], v[162:165], v[194:197], v[70:73]
	s_barrier
	s_add_i32 s10, s75, s43
	v_lshl_add_u64 v[210:211], s[34:35], 0, v[32:33]
	s_mov_b32 m0, s10
	ds_read_b128 v[166:169], v244 offset:16384
	ds_read_b128 v[170:173], v244 offset:17408
	ds_read_b128 v[174:177], v244 offset:18432
	ds_read_b128 v[178:181], v244 offset:19456
	ds_read_b128 v[182:185], v244 offset:20480
	ds_read_b128 v[186:189], v244 offset:21504
	ds_read_b128 v[190:193], v244 offset:22528
	ds_read_b128 v[194:197], v244 offset:23552
	global_load_lds_dwordx4 v[210:211], off
	s_add_i32 m0, s10, 0x2000
	s_add_u32 s10, s34, 0x50000
	v_lshl_add_u64 v[212:213], s[34:35], 0, v[34:35]
	s_addc_u32 s11, s35, 0
	s_add_i32 s75, s76, s43
	global_load_lds_dwordx4 v[212:213], off
	v_lshl_add_u64 v[214:215], s[10:11], 0, v[32:33]
	s_mov_b32 m0, s75
	v_lshl_add_u64 v[218:219], s[38:39], 0, v[198:199]
	global_load_lds_dwordx4 v[214:215], off
	v_lshl_add_u64 v[214:215], s[10:11], 0, v[34:35]
	s_add_i32 m0, s75, 0x2000
	s_nop 0
	global_load_lds_dwordx4 v[214:215], off
	v_lshl_add_u64 v[214:215], s[38:39], 0, v[202:203]
	s_mov_b32 m0, s46
	s_nop 0
	global_load_lds_dwordx4 v[214:215], off
	s_mov_b32 m0, s47
	s_nop 0
	global_load_lds_dwordx4 v[218:219], off
	s_waitcnt vmcnt(8)
	s_waitcnt lgkmcnt(0)
	s_barrier
	s_waitcnt lgkmcnt(0)
	v_mfma_f32_16x16x32_bf16 v[66:69], v[134:137], v[166:169], v[66:69]
	v_mfma_f32_16x16x32_bf16 v[62:65], v[142:145], v[166:169], v[62:65]
	v_mfma_f32_16x16x32_bf16 v[58:61], v[134:137], v[174:177], v[58:61]
	v_mfma_f32_16x16x32_bf16 v[54:57], v[142:145], v[174:177], v[54:57]
	v_mfma_f32_16x16x32_bf16 v[50:53], v[134:137], v[182:185], v[50:53]
	v_mfma_f32_16x16x32_bf16 v[46:49], v[142:145], v[182:185], v[46:49]
	v_mfma_f32_16x16x32_bf16 v[42:45], v[134:137], v[190:193], v[42:45]
	v_mfma_f32_16x16x32_bf16 v[38:41], v[142:145], v[190:193], v[38:41]
	v_mfma_f32_16x16x32_bf16 v[66:69], v[138:141], v[170:173], v[66:69]
	v_mfma_f32_16x16x32_bf16 v[62:65], v[146:149], v[170:173], v[62:65]
	v_mfma_f32_16x16x32_bf16 v[58:61], v[138:141], v[178:181], v[58:61]
	v_mfma_f32_16x16x32_bf16 v[54:57], v[146:149], v[178:181], v[54:57]
	v_mfma_f32_16x16x32_bf16 v[50:53], v[138:141], v[186:189], v[50:53]
	v_mfma_f32_16x16x32_bf16 v[46:49], v[146:149], v[186:189], v[46:49]
	v_mfma_f32_16x16x32_bf16 v[42:45], v[138:141], v[194:197], v[42:45]
	v_mfma_f32_16x16x32_bf16 v[38:41], v[146:149], v[194:197], v[38:41]
	v_mfma_f32_16x16x32_bf16 v[28:31], v[150:153], v[166:169], v[28:31]
	v_mfma_f32_16x16x32_bf16 v[24:27], v[158:161], v[166:169], v[24:27]
	v_mfma_f32_16x16x32_bf16 v[20:23], v[150:153], v[174:177], v[20:23]
	v_mfma_f32_16x16x32_bf16 v[16:19], v[158:161], v[174:177], v[16:19]
	v_mfma_f32_16x16x32_bf16 v[12:15], v[150:153], v[182:185], v[12:15]
	v_mfma_f32_16x16x32_bf16 v[8:11], v[158:161], v[182:185], v[8:11]
	v_mfma_f32_16x16x32_bf16 v[4:7], v[150:153], v[190:193], v[4:7]
	v_mfma_f32_16x16x32_bf16 v[0:3], v[158:161], v[190:193], v[0:3]
	v_mfma_f32_16x16x32_bf16 v[28:31], v[154:157], v[170:173], v[28:31]
	v_mfma_f32_16x16x32_bf16 v[24:27], v[162:165], v[170:173], v[24:27]
	v_mfma_f32_16x16x32_bf16 v[20:23], v[154:157], v[178:181], v[20:23]
	v_mfma_f32_16x16x32_bf16 v[16:19], v[162:165], v[178:181], v[16:19]
	v_mfma_f32_16x16x32_bf16 v[12:15], v[154:157], v[186:189], v[12:15]
	v_mfma_f32_16x16x32_bf16 v[8:11], v[162:165], v[186:189], v[8:11]
	v_mfma_f32_16x16x32_bf16 v[4:7], v[154:157], v[194:197], v[4:7]
	v_mfma_f32_16x16x32_bf16 v[0:3], v[162:165], v[194:197], v[0:3]
	s_barrier
	s_add_i32 s75, 0, 0x18000
	s_add_i32 s76, 0, 0x1c000
	v_add_u32_e32 v146, s75, v201
	v_add_u32_e32 v162, s76, v201
	ds_read_b128 v[134:137], v146
	ds_read_b128 v[138:141], v146 offset:1024
	ds_read_b128 v[142:145], v146 offset:2048
	ds_read_b128 v[146:149], v146 offset:3072
	ds_read_b128 v[150:153], v162
	ds_read_b128 v[154:157], v162 offset:1024
	ds_read_b128 v[158:161], v162 offset:2048
	ds_read_b128 v[162:165], v162 offset:3072
	s_add_u32 s10, s38, 0x50000
	s_addc_u32 s11, s39, 0
	s_mov_b32 m0, s52
	v_lshl_add_u64 v[220:221], s[10:11], 0, v[202:203]
	ds_read_b128 v[166:169], v244 offset:32768
	ds_read_b128 v[170:173], v244 offset:33792
	ds_read_b128 v[174:177], v244 offset:34816
	ds_read_b128 v[178:181], v244 offset:35840
	ds_read_b128 v[182:185], v244 offset:36864
	ds_read_b128 v[186:189], v244 offset:37888
	ds_read_b128 v[190:193], v244 offset:38912
	ds_read_b128 v[194:197], v244 offset:39936
	global_load_lds_dwordx4 v[220:221], off
	v_lshl_add_u64 v[220:221], s[10:11], 0, v[198:199]
	s_mov_b32 m0, s53
	s_nop 0
	global_load_lds_dwordx4 v[220:221], off
	s_waitcnt vmcnt(8)
	s_waitcnt lgkmcnt(0)
	s_barrier
	s_waitcnt lgkmcnt(0)
	v_mfma_f32_16x16x32_bf16 v[130:133], v[134:137], v[166:169], v[130:133]
	v_mfma_f32_16x16x32_bf16 v[126:129], v[142:145], v[166:169], v[126:129]
	v_mfma_f32_16x16x32_bf16 v[122:125], v[134:137], v[174:177], v[122:125]
	v_mfma_f32_16x16x32_bf16 v[118:121], v[142:145], v[174:177], v[118:121]
	v_mfma_f32_16x16x32_bf16 v[114:117], v[134:137], v[182:185], v[114:117]
	v_mfma_f32_16x16x32_bf16 v[110:113], v[142:145], v[182:185], v[110:113]
	v_mfma_f32_16x16x32_bf16 v[106:109], v[134:137], v[190:193], v[106:109]
	v_mfma_f32_16x16x32_bf16 v[102:105], v[142:145], v[190:193], v[102:105]
	v_mfma_f32_16x16x32_bf16 v[130:133], v[138:141], v[170:173], v[130:133]
	v_mfma_f32_16x16x32_bf16 v[126:129], v[146:149], v[170:173], v[126:129]
	v_mfma_f32_16x16x32_bf16 v[122:125], v[138:141], v[178:181], v[122:125]
	v_mfma_f32_16x16x32_bf16 v[118:121], v[146:149], v[178:181], v[118:121]
	v_mfma_f32_16x16x32_bf16 v[114:117], v[138:141], v[186:189], v[114:117]
	v_mfma_f32_16x16x32_bf16 v[110:113], v[146:149], v[186:189], v[110:113]
	v_mfma_f32_16x16x32_bf16 v[106:109], v[138:141], v[194:197], v[106:109]
	v_mfma_f32_16x16x32_bf16 v[102:105], v[146:149], v[194:197], v[102:105]
	v_mfma_f32_16x16x32_bf16 v[98:101], v[150:153], v[166:169], v[98:101]
	v_mfma_f32_16x16x32_bf16 v[94:97], v[158:161], v[166:169], v[94:97]
	v_mfma_f32_16x16x32_bf16 v[90:93], v[150:153], v[174:177], v[90:93]
	v_mfma_f32_16x16x32_bf16 v[86:89], v[158:161], v[174:177], v[86:89]
	v_mfma_f32_16x16x32_bf16 v[82:85], v[150:153], v[182:185], v[82:85]
	v_mfma_f32_16x16x32_bf16 v[78:81], v[158:161], v[182:185], v[78:81]
	v_mfma_f32_16x16x32_bf16 v[74:77], v[150:153], v[190:193], v[74:77]
	v_mfma_f32_16x16x32_bf16 v[70:73], v[158:161], v[190:193], v[70:73]
	v_mfma_f32_16x16x32_bf16 v[98:101], v[154:157], v[170:173], v[98:101]
	v_mfma_f32_16x16x32_bf16 v[94:97], v[162:165], v[170:173], v[94:97]
	v_mfma_f32_16x16x32_bf16 v[90:93], v[154:157], v[178:181], v[90:93]
	v_mfma_f32_16x16x32_bf16 v[86:89], v[162:165], v[178:181], v[86:89]
	v_mfma_f32_16x16x32_bf16 v[82:85], v[154:157], v[186:189], v[82:85]
	v_mfma_f32_16x16x32_bf16 v[78:81], v[162:165], v[186:189], v[78:81]
	v_mfma_f32_16x16x32_bf16 v[74:77], v[154:157], v[194:197], v[74:77]
	v_mfma_f32_16x16x32_bf16 v[70:73], v[162:165], v[194:197], v[70:73]
	s_barrier
	s_add_i32 s10, s75, s43
	v_lshl_add_u64 v[210:211], v[210:211], 0, s[68:69]
	s_mov_b32 m0, s10
	ds_read_b128 v[166:169], v244 offset:49152
	ds_read_b128 v[170:173], v244 offset:50176
	ds_read_b128 v[174:177], v244 offset:51200
	ds_read_b128 v[178:181], v244 offset:52224
	ds_read_b128 v[182:185], v244 offset:53248
	ds_read_b128 v[186:189], v244 offset:54272
	ds_read_b128 v[190:193], v244 offset:55296
	ds_read_b128 v[194:197], v244 offset:56320
	global_load_lds_dwordx4 v[210:211], off
	s_add_i32 m0, s10, 0x2000
	s_add_u32 s10, s34, 0x50080
	v_lshl_add_u64 v[210:211], v[212:213], 0, s[68:69]
	s_addc_u32 s11, s35, 0
	s_add_i32 s34, s76, s43
	global_load_lds_dwordx4 v[210:211], off
	v_lshl_add_u64 v[210:211], s[10:11], 0, v[32:33]
	s_mov_b32 m0, s34
	s_nop 0
	global_load_lds_dwordx4 v[210:211], off
	v_lshl_add_u64 v[210:211], s[10:11], 0, v[34:35]
	s_add_i32 m0, s34, 0x2000
	s_nop 0
	global_load_lds_dwordx4 v[210:211], off
	v_lshl_add_u64 v[210:211], v[214:215], 0, s[68:69]
	s_mov_b32 m0, s57
	s_nop 0
	global_load_lds_dwordx4 v[210:211], off
	v_lshl_add_u64 v[210:211], v[218:219], 0, s[68:69]
	s_mov_b32 m0, s61
	s_nop 0
	global_load_lds_dwordx4 v[210:211], off
	s_waitcnt vmcnt(8)
	s_waitcnt lgkmcnt(0)
	s_barrier
	s_waitcnt lgkmcnt(0)
	v_mfma_f32_16x16x32_bf16 v[66:69], v[134:137], v[166:169], v[66:69]
	v_mfma_f32_16x16x32_bf16 v[62:65], v[142:145], v[166:169], v[62:65]
	v_mfma_f32_16x16x32_bf16 v[58:61], v[134:137], v[174:177], v[58:61]
	v_mfma_f32_16x16x32_bf16 v[54:57], v[142:145], v[174:177], v[54:57]
	v_mfma_f32_16x16x32_bf16 v[50:53], v[134:137], v[182:185], v[50:53]
	v_mfma_f32_16x16x32_bf16 v[46:49], v[142:145], v[182:185], v[46:49]
	v_mfma_f32_16x16x32_bf16 v[42:45], v[134:137], v[190:193], v[42:45]
	v_mfma_f32_16x16x32_bf16 v[38:41], v[142:145], v[190:193], v[38:41]
	v_mfma_f32_16x16x32_bf16 v[66:69], v[138:141], v[170:173], v[66:69]
	v_mfma_f32_16x16x32_bf16 v[62:65], v[146:149], v[170:173], v[62:65]
	v_mfma_f32_16x16x32_bf16 v[58:61], v[138:141], v[178:181], v[58:61]
	v_mfma_f32_16x16x32_bf16 v[54:57], v[146:149], v[178:181], v[54:57]
	v_mfma_f32_16x16x32_bf16 v[50:53], v[138:141], v[186:189], v[50:53]
	v_mfma_f32_16x16x32_bf16 v[46:49], v[146:149], v[186:189], v[46:49]
	v_mfma_f32_16x16x32_bf16 v[42:45], v[138:141], v[194:197], v[42:45]
	v_mfma_f32_16x16x32_bf16 v[38:41], v[146:149], v[194:197], v[38:41]
	v_mfma_f32_16x16x32_bf16 v[28:31], v[150:153], v[166:169], v[28:31]
	v_mfma_f32_16x16x32_bf16 v[24:27], v[158:161], v[166:169], v[24:27]
	v_mfma_f32_16x16x32_bf16 v[20:23], v[150:153], v[174:177], v[20:23]
	v_mfma_f32_16x16x32_bf16 v[16:19], v[158:161], v[174:177], v[16:19]
	v_mfma_f32_16x16x32_bf16 v[12:15], v[150:153], v[182:185], v[12:15]
	v_mfma_f32_16x16x32_bf16 v[8:11], v[158:161], v[182:185], v[8:11]
	v_mfma_f32_16x16x32_bf16 v[4:7], v[150:153], v[190:193], v[4:7]
	v_mfma_f32_16x16x32_bf16 v[0:3], v[158:161], v[190:193], v[0:3]
	v_mfma_f32_16x16x32_bf16 v[28:31], v[154:157], v[170:173], v[28:31]
	v_mfma_f32_16x16x32_bf16 v[24:27], v[162:165], v[170:173], v[24:27]
	v_mfma_f32_16x16x32_bf16 v[20:23], v[154:157], v[178:181], v[20:23]
	v_mfma_f32_16x16x32_bf16 v[16:19], v[162:165], v[178:181], v[16:19]
	v_mfma_f32_16x16x32_bf16 v[12:15], v[154:157], v[186:189], v[12:15]
	v_mfma_f32_16x16x32_bf16 v[8:11], v[162:165], v[186:189], v[8:11]
	v_mfma_f32_16x16x32_bf16 v[4:7], v[154:157], v[194:197], v[4:7]
	v_mfma_f32_16x16x32_bf16 v[0:3], v[162:165], v[194:197], v[0:3]
	s_barrier
	s_add_u32 s29, s29, 0x100
	s_addc_u32 s54, s54, 0
	s_cmp_ge_i32 s74, s66
	s_mov_b64 s[10:11], s[12:13]
	s_mov_b32 s34, s74
	s_cbranch_scc0 .LBB0_899
	s_and_b64 vcc, exec, s[26:27]
	s_cbranch_vccz .LBB0_902
	s_barrier

.LBB0_1540:
.LBB0_1541:
	s_or_b32 s92, s55, 1
	s_lshl_b64 s[74:75], s[92:93], 7
	s_add_u32 s0, s46, s74
	s_addc_u32 s54, s47, s75
	s_add_i32 s92, s55, 2
	s_lshl_b64 s[76:77], s[92:93], 7
	s_add_u32 s78, s46, s76
	s_addc_u32 s79, s47, s77
	s_and_b64 s[74:75], s[34:35], exec
	s_cselect_b32 s75, s49, s79
	s_cselect_b32 s74, s90, s78
	s_add_u32 s76, s8, s76
	s_addc_u32 s77, s9, s77
	s_and_b64 s[34:35], s[34:35], exec
	s_cselect_b32 s35, s53, s77
	s_cselect_b32 s34, s91, s76
	s_add_i32 s78, 0, 0x10000
	v_add_u32_e32 v148, s78, v138
	s_add_i32 s79, 0, 0x14000
	ds_read_b128 v[140:143], v148
	ds_read_b128 v[144:147], v148 offset:1024
	ds_read_b128 v[156:159], v148 offset:2048
	ds_read_b128 v[160:163], v148 offset:3072
	v_add_u32_e32 v148, s79, v138
	ds_read_b128 v[164:167], v148
	ds_read_b128 v[168:171], v148 offset:1024
	ds_read_b128 v[172:175], v148 offset:2048
	ds_read_b128 v[176:179], v148 offset:3072
	s_add_u32 s76, s0, 0x40000
	s_addc_u32 s77, s54, 0
	v_lshl_add_u64 v[148:149], s[76:77], 0, v[134:135]
	s_add_i32 m0, s83, 0xc000
	ds_read_b128 v[180:183], v139
	ds_read_b128 v[184:187], v139 offset:1024
	ds_read_b128 v[188:191], v139 offset:2048
	ds_read_b128 v[192:195], v139 offset:3072
	ds_read_b128 v[196:199], v139 offset:4096
	ds_read_b128 v[202:205], v139 offset:5120
	ds_read_b128 v[206:209], v139 offset:6144
	ds_read_b128 v[210:213], v139 offset:7168
	global_load_lds_dwordx4 v[148:149], off
	v_lshl_add_u64 v[148:149], s[76:77], 0, v[136:137]
	s_add_i32 m0, s83, 0xe000
	s_nop 0
	global_load_lds_dwordx4 v[148:149], off
	s_waitcnt vmcnt(8)
	s_waitcnt lgkmcnt(0)
	s_barrier
	s_waitcnt lgkmcnt(0)
	v_mfma_f32_16x16x32_bf16 v[130:133], v[140:143], v[180:183], v[130:133]
	v_mfma_f32_16x16x32_bf16 v[126:129], v[156:159], v[180:183], v[126:129]
	v_mfma_f32_16x16x32_bf16 v[122:125], v[140:143], v[188:191], v[122:125]
	v_mfma_f32_16x16x32_bf16 v[118:121], v[156:159], v[188:191], v[118:121]
	v_mfma_f32_16x16x32_bf16 v[114:117], v[140:143], v[196:199], v[114:117]
	v_mfma_f32_16x16x32_bf16 v[110:113], v[156:159], v[196:199], v[110:113]
	v_mfma_f32_16x16x32_bf16 v[106:109], v[140:143], v[206:209], v[106:109]
	v_mfma_f32_16x16x32_bf16 v[102:105], v[156:159], v[206:209], v[102:105]
	v_mfma_f32_16x16x32_bf16 v[130:133], v[144:147], v[184:187], v[130:133]
	v_mfma_f32_16x16x32_bf16 v[126:129], v[160:163], v[184:187], v[126:129]
	v_mfma_f32_16x16x32_bf16 v[122:125], v[144:147], v[192:195], v[122:125]
	v_mfma_f32_16x16x32_bf16 v[118:121], v[160:163], v[192:195], v[118:121]
	v_mfma_f32_16x16x32_bf16 v[114:117], v[144:147], v[202:205], v[114:117]
	v_mfma_f32_16x16x32_bf16 v[110:113], v[160:163], v[202:205], v[110:113]
	v_mfma_f32_16x16x32_bf16 v[106:109], v[144:147], v[210:213], v[106:109]
	v_mfma_f32_16x16x32_bf16 v[102:105], v[160:163], v[210:213], v[102:105]
	v_mfma_f32_16x16x32_bf16 v[86:89], v[164:167], v[180:183], v[86:89]
	v_mfma_f32_16x16x32_bf16 v[78:81], v[172:175], v[180:183], v[78:81]
	v_mfma_f32_16x16x32_bf16 v[74:77], v[164:167], v[188:191], v[74:77]
	v_mfma_f32_16x16x32_bf16 v[66:69], v[172:175], v[188:191], v[66:69]
	v_mfma_f32_16x16x32_bf16 v[58:61], v[164:167], v[196:199], v[58:61]
	v_mfma_f32_16x16x32_bf16 v[54:57], v[172:175], v[196:199], v[54:57]
	v_mfma_f32_16x16x32_bf16 v[42:45], v[164:167], v[206:209], v[42:45]
	v_mfma_f32_16x16x32_bf16 v[38:41], v[172:175], v[206:209], v[38:41]
	v_mfma_f32_16x16x32_bf16 v[86:89], v[168:171], v[184:187], v[86:89]
	v_mfma_f32_16x16x32_bf16 v[78:81], v[176:179], v[184:187], v[78:81]
	v_mfma_f32_16x16x32_bf16 v[74:77], v[168:171], v[192:195], v[74:77]
	v_mfma_f32_16x16x32_bf16 v[66:69], v[176:179], v[192:195], v[66:69]
	v_mfma_f32_16x16x32_bf16 v[58:61], v[168:171], v[202:205], v[58:61]
	v_mfma_f32_16x16x32_bf16 v[54:57], v[176:179], v[202:205], v[54:57]
	v_mfma_f32_16x16x32_bf16 v[42:45], v[168:171], v[210:213], v[42:45]
	v_mfma_f32_16x16x32_bf16 v[38:41], v[176:179], v[210:213], v[38:41]
	s_barrier
	s_add_i32 s0, s78, s82
	v_lshl_add_u64 v[148:149], s[34:35], 0, v[32:33]
	s_mov_b32 m0, s0
	ds_read_b128 v[180:183], v139 offset:16384
	ds_read_b128 v[184:187], v139 offset:17408
	ds_read_b128 v[188:191], v139 offset:18432
	ds_read_b128 v[192:195], v139 offset:19456
	ds_read_b128 v[196:199], v139 offset:20480
	ds_read_b128 v[202:205], v139 offset:21504
	ds_read_b128 v[206:209], v139 offset:22528
	ds_read_b128 v[210:213], v139 offset:23552
	global_load_lds_dwordx4 v[148:149], off
	s_add_i32 m0, s0, 0x2000
	s_add_u32 s76, s34, 0x40000
	v_lshl_add_u64 v[214:215], s[34:35], 0, v[34:35]
	s_addc_u32 s77, s35, 0
	s_add_i32 s0, s79, s82
	global_load_lds_dwordx4 v[214:215], off
	v_lshl_add_u64 v[218:219], s[76:77], 0, v[32:33]
	s_mov_b32 m0, s0
	v_lshl_add_u64 v[220:221], s[74:75], 0, v[136:137]
	global_load_lds_dwordx4 v[218:219], off
	v_lshl_add_u64 v[218:219], s[76:77], 0, v[34:35]
	s_add_i32 m0, s0, 0x2000
	s_nop 0
	global_load_lds_dwordx4 v[218:219], off
	v_lshl_add_u64 v[218:219], s[74:75], 0, v[134:135]
	s_mov_b32 m0, s83
	s_nop 0
	global_load_lds_dwordx4 v[218:219], off
	s_mov_b32 m0, s86
	s_nop 0
	global_load_lds_dwordx4 v[220:221], off
	s_waitcnt vmcnt(8)
	s_waitcnt lgkmcnt(0)
	s_barrier
	s_waitcnt lgkmcnt(0)
	v_mfma_f32_16x16x32_bf16 v[98:101], v[140:143], v[180:183], v[98:101]
	v_mfma_f32_16x16x32_bf16 v[94:97], v[156:159], v[180:183], v[94:97]
	v_mfma_f32_16x16x32_bf16 v[90:93], v[140:143], v[188:191], v[90:93]
	v_mfma_f32_16x16x32_bf16 v[82:85], v[156:159], v[188:191], v[82:85]
	v_mfma_f32_16x16x32_bf16 v[70:73], v[140:143], v[196:199], v[70:73]
	v_mfma_f32_16x16x32_bf16 v[62:65], v[156:159], v[196:199], v[62:65]
	v_mfma_f32_16x16x32_bf16 v[50:53], v[140:143], v[206:209], v[50:53]
	v_mfma_f32_16x16x32_bf16 v[46:49], v[156:159], v[206:209], v[46:49]
	v_mfma_f32_16x16x32_bf16 v[98:101], v[144:147], v[184:187], v[98:101]
	v_mfma_f32_16x16x32_bf16 v[94:97], v[160:163], v[184:187], v[94:97]
	v_mfma_f32_16x16x32_bf16 v[90:93], v[144:147], v[192:195], v[90:93]
	v_mfma_f32_16x16x32_bf16 v[82:85], v[160:163], v[192:195], v[82:85]
	v_mfma_f32_16x16x32_bf16 v[70:73], v[144:147], v[202:205], v[70:73]
	v_mfma_f32_16x16x32_bf16 v[62:65], v[160:163], v[202:205], v[62:65]
	v_mfma_f32_16x16x32_bf16 v[50:53], v[144:147], v[210:213], v[50:53]
	v_mfma_f32_16x16x32_bf16 v[46:49], v[160:163], v[210:213], v[46:49]
	v_mfma_f32_16x16x32_bf16 v[28:31], v[164:167], v[180:183], v[28:31]
	v_mfma_f32_16x16x32_bf16 v[24:27], v[172:175], v[180:183], v[24:27]
	v_mfma_f32_16x16x32_bf16 v[20:23], v[164:167], v[188:191], v[20:23]
	v_mfma_f32_16x16x32_bf16 v[16:19], v[172:175], v[188:191], v[16:19]
	v_mfma_f32_16x16x32_bf16 v[12:15], v[164:167], v[196:199], v[12:15]
	v_mfma_f32_16x16x32_bf16 v[8:11], v[172:175], v[196:199], v[8:11]
	v_mfma_f32_16x16x32_bf16 v[4:7], v[164:167], v[206:209], v[4:7]
	v_mfma_f32_16x16x32_bf16 v[0:3], v[172:175], v[206:209], v[0:3]
	v_mfma_f32_16x16x32_bf16 v[28:31], v[168:171], v[184:187], v[28:31]
	v_mfma_f32_16x16x32_bf16 v[24:27], v[176:179], v[184:187], v[24:27]
	v_mfma_f32_16x16x32_bf16 v[20:23], v[168:171], v[192:195], v[20:23]
	v_mfma_f32_16x16x32_bf16 v[16:19], v[176:179], v[192:195], v[16:19]
	v_mfma_f32_16x16x32_bf16 v[12:15], v[168:171], v[202:205], v[12:15]
	v_mfma_f32_16x16x32_bf16 v[8:11], v[176:179], v[202:205], v[8:11]
	v_mfma_f32_16x16x32_bf16 v[4:7], v[168:171], v[210:213], v[4:7]
	v_mfma_f32_16x16x32_bf16 v[0:3], v[176:179], v[210:213], v[0:3]
	s_barrier
	s_add_i32 s0, 0, 0x18000
	v_add_u32_e32 v150, s0, v138
	s_add_i32 s54, 0, 0x1c000
	ds_read_b128 v[140:143], v150
	ds_read_b128 v[144:147], v150 offset:1024
	ds_read_b128 v[156:159], v150 offset:2048
	ds_read_b128 v[160:163], v150 offset:3072
	v_add_u32_e32 v150, s54, v138
	ds_read_b128 v[164:167], v150
	ds_read_b128 v[168:171], v150 offset:1024
	ds_read_b128 v[172:175], v150 offset:2048
	ds_read_b128 v[176:179], v150 offset:3072
	s_add_u32 s74, s74, 0x40000
	s_addc_u32 s75, s75, 0
	s_mov_b32 m0, s87
	v_lshl_add_u64 v[222:223], s[74:75], 0, v[134:135]
	ds_read_b128 v[180:183], v139 offset:32768
	ds_read_b128 v[184:187], v139 offset:33792
	ds_read_b128 v[188:191], v139 offset:34816
	ds_read_b128 v[192:195], v139 offset:35840
	ds_read_b128 v[196:199], v139 offset:36864
	ds_read_b128 v[202:205], v139 offset:37888
	ds_read_b128 v[206:209], v139 offset:38912
	ds_read_b128 v[210:213], v139 offset:39936
	global_load_lds_dwordx4 v[222:223], off
	v_lshl_add_u64 v[222:223], s[74:75], 0, v[136:137]
	s_mov_b32 m0, s88
	s_nop 0
	global_load_lds_dwordx4 v[222:223], off
	s_waitcnt vmcnt(8)
	s_waitcnt lgkmcnt(0)
	s_barrier
	s_waitcnt lgkmcnt(0)
	v_mfma_f32_16x16x32_bf16 v[130:133], v[140:143], v[180:183], v[130:133]
	v_mfma_f32_16x16x32_bf16 v[126:129], v[156:159], v[180:183], v[126:129]
	v_mfma_f32_16x16x32_bf16 v[122:125], v[140:143], v[188:191], v[122:125]
	v_mfma_f32_16x16x32_bf16 v[118:121], v[156:159], v[188:191], v[118:121]
	v_mfma_f32_16x16x32_bf16 v[114:117], v[140:143], v[196:199], v[114:117]
	v_mfma_f32_16x16x32_bf16 v[110:113], v[156:159], v[196:199], v[110:113]
	v_mfma_f32_16x16x32_bf16 v[106:109], v[140:143], v[206:209], v[106:109]
	v_mfma_f32_16x16x32_bf16 v[102:105], v[156:159], v[206:209], v[102:105]
	v_mfma_f32_16x16x32_bf16 v[130:133], v[144:147], v[184:187], v[130:133]
	v_mfma_f32_16x16x32_bf16 v[126:129], v[160:163], v[184:187], v[126:129]
	v_mfma_f32_16x16x32_bf16 v[122:125], v[144:147], v[192:195], v[122:125]
	v_mfma_f32_16x16x32_bf16 v[118:121], v[160:163], v[192:195], v[118:121]
	v_mfma_f32_16x16x32_bf16 v[114:117], v[144:147], v[202:205], v[114:117]
	v_mfma_f32_16x16x32_bf16 v[110:113], v[160:163], v[202:205], v[110:113]
	v_mfma_f32_16x16x32_bf16 v[106:109], v[144:147], v[210:213], v[106:109]
	v_mfma_f32_16x16x32_bf16 v[102:105], v[160:163], v[210:213], v[102:105]
	v_mfma_f32_16x16x32_bf16 v[86:89], v[164:167], v[180:183], v[86:89]
	v_mfma_f32_16x16x32_bf16 v[78:81], v[172:175], v[180:183], v[78:81]
	v_mfma_f32_16x16x32_bf16 v[74:77], v[164:167], v[188:191], v[74:77]
	v_mfma_f32_16x16x32_bf16 v[66:69], v[172:175], v[188:191], v[66:69]
	v_mfma_f32_16x16x32_bf16 v[58:61], v[164:167], v[196:199], v[58:61]
	v_mfma_f32_16x16x32_bf16 v[54:57], v[172:175], v[196:199], v[54:57]
	v_mfma_f32_16x16x32_bf16 v[42:45], v[164:167], v[206:209], v[42:45]
	v_mfma_f32_16x16x32_bf16 v[38:41], v[172:175], v[206:209], v[38:41]
	v_mfma_f32_16x16x32_bf16 v[86:89], v[168:171], v[184:187], v[86:89]
	v_mfma_f32_16x16x32_bf16 v[78:81], v[176:179], v[184:187], v[78:81]
	v_mfma_f32_16x16x32_bf16 v[74:77], v[168:171], v[192:195], v[74:77]
	v_mfma_f32_16x16x32_bf16 v[66:69], v[176:179], v[192:195], v[66:69]
	v_mfma_f32_16x16x32_bf16 v[58:61], v[168:171], v[202:205], v[58:61]
	v_mfma_f32_16x16x32_bf16 v[54:57], v[176:179], v[202:205], v[54:57]
	v_mfma_f32_16x16x32_bf16 v[42:45], v[168:171], v[210:213], v[42:45]
	v_mfma_f32_16x16x32_bf16 v[38:41], v[176:179], v[210:213], v[38:41]
	s_barrier
	s_add_i32 s0, s0, s82
	v_lshl_add_u64 v[148:149], v[148:149], 0, s[68:69]
	s_mov_b32 m0, s0
	ds_read_b128 v[180:183], v139 offset:49152
	ds_read_b128 v[184:187], v139 offset:50176
	ds_read_b128 v[188:191], v139 offset:51200
	ds_read_b128 v[192:195], v139 offset:52224
	ds_read_b128 v[196:199], v139 offset:53248
	ds_read_b128 v[202:205], v139 offset:54272
	ds_read_b128 v[206:209], v139 offset:55296
	ds_read_b128 v[210:213], v139 offset:56320
	global_load_lds_dwordx4 v[148:149], off
	s_add_i32 m0, s0, 0x2000
	s_add_u32 s34, s34, 0x40080
	v_lshl_add_u64 v[148:149], v[214:215], 0, s[68:69]
	s_addc_u32 s35, s35, 0
	s_add_i32 s0, s54, s82
	global_load_lds_dwordx4 v[148:149], off
	v_lshl_add_u64 v[148:149], s[34:35], 0, v[32:33]
	s_mov_b32 m0, s0
	s_nop 0
	global_load_lds_dwordx4 v[148:149], off
	v_lshl_add_u64 v[148:149], s[34:35], 0, v[34:35]
	s_add_i32 m0, s0, 0x2000
	s_nop 0
	global_load_lds_dwordx4 v[148:149], off
	v_lshl_add_u64 v[148:149], v[218:219], 0, s[68:69]
	s_mov_b32 m0, s89
	s_nop 0
	global_load_lds_dwordx4 v[148:149], off
	v_lshl_add_u64 v[148:149], v[220:221], 0, s[68:69]
	s_mov_b32 m0, s94
	s_nop 0
	global_load_lds_dwordx4 v[148:149], off
	s_waitcnt vmcnt(8)
	s_waitcnt lgkmcnt(0)
	s_barrier
	s_waitcnt lgkmcnt(0)
	v_mfma_f32_16x16x32_bf16 v[98:101], v[140:143], v[180:183], v[98:101]
	v_mfma_f32_16x16x32_bf16 v[94:97], v[156:159], v[180:183], v[94:97]
	v_mfma_f32_16x16x32_bf16 v[90:93], v[140:143], v[188:191], v[90:93]
	v_mfma_f32_16x16x32_bf16 v[82:85], v[156:159], v[188:191], v[82:85]
	v_mfma_f32_16x16x32_bf16 v[70:73], v[140:143], v[196:199], v[70:73]
	v_mfma_f32_16x16x32_bf16 v[62:65], v[156:159], v[196:199], v[62:65]
	v_mfma_f32_16x16x32_bf16 v[50:53], v[140:143], v[206:209], v[50:53]
	v_mfma_f32_16x16x32_bf16 v[46:49], v[156:159], v[206:209], v[46:49]
	v_mfma_f32_16x16x32_bf16 v[98:101], v[144:147], v[184:187], v[98:101]
	v_mfma_f32_16x16x32_bf16 v[94:97], v[160:163], v[184:187], v[94:97]
	v_mfma_f32_16x16x32_bf16 v[90:93], v[144:147], v[192:195], v[90:93]
	v_mfma_f32_16x16x32_bf16 v[82:85], v[160:163], v[192:195], v[82:85]
	v_mfma_f32_16x16x32_bf16 v[70:73], v[144:147], v[202:205], v[70:73]
	v_mfma_f32_16x16x32_bf16 v[62:65], v[160:163], v[202:205], v[62:65]
	v_mfma_f32_16x16x32_bf16 v[50:53], v[144:147], v[210:213], v[50:53]
	v_mfma_f32_16x16x32_bf16 v[46:49], v[160:163], v[210:213], v[46:49]
	v_mfma_f32_16x16x32_bf16 v[28:31], v[164:167], v[180:183], v[28:31]
	v_mfma_f32_16x16x32_bf16 v[24:27], v[172:175], v[180:183], v[24:27]
	v_mfma_f32_16x16x32_bf16 v[20:23], v[164:167], v[188:191], v[20:23]
	v_mfma_f32_16x16x32_bf16 v[16:19], v[172:175], v[188:191], v[16:19]
	v_mfma_f32_16x16x32_bf16 v[12:15], v[164:167], v[196:199], v[12:15]
	v_mfma_f32_16x16x32_bf16 v[8:11], v[172:175], v[196:199], v[8:11]
	v_mfma_f32_16x16x32_bf16 v[4:7], v[164:167], v[206:209], v[4:7]
	v_mfma_f32_16x16x32_bf16 v[0:3], v[172:175], v[206:209], v[0:3]
	v_mfma_f32_16x16x32_bf16 v[28:31], v[168:171], v[184:187], v[28:31]
	v_mfma_f32_16x16x32_bf16 v[24:27], v[176:179], v[184:187], v[24:27]
	v_mfma_f32_16x16x32_bf16 v[20:23], v[168:171], v[192:195], v[20:23]
	v_mfma_f32_16x16x32_bf16 v[16:19], v[176:179], v[192:195], v[16:19]
	v_mfma_f32_16x16x32_bf16 v[12:15], v[168:171], v[202:205], v[12:15]
	v_mfma_f32_16x16x32_bf16 v[8:11], v[176:179], v[202:205], v[8:11]
	v_mfma_f32_16x16x32_bf16 v[4:7], v[168:171], v[210:213], v[4:7]
	v_mfma_f32_16x16x32_bf16 v[0:3], v[176:179], v[210:213], v[0:3]
	s_barrier
	s_cmp_gt_u32 s55, 13
	s_cbranch_scc1 .LBB0_1543
	s_mov_b32 s55, s92
	s_branch .LBB0_1508

.LBB0_1630:
.LBB0_1631:
	s_or_b32 s92, s55, 1
	s_lshl_b64 s[70:71], s[92:93], 7
	s_add_u32 s0, s10, s70
	s_addc_u32 s54, s11, s71
	s_add_i32 s92, s55, 2
	s_lshl_b64 s[72:73], s[92:93], 7
	s_add_u32 s74, s10, s72
	s_addc_u32 s75, s11, s73
	s_and_b64 s[70:71], s[34:35], exec
	s_cselect_b32 s71, s13, s75
	s_cselect_b32 s70, s89, s74
	s_add_u32 s72, s8, s72
	s_addc_u32 s73, s9, s73
	s_and_b64 s[34:35], s[34:35], exec
	s_cselect_b32 s35, s47, s73
	s_cselect_b32 s34, s90, s72
	s_add_i32 s74, 0, 0x10000
	v_add_u32_e32 v153, s74, v138
	s_add_i32 s75, 0, 0x14000
	ds_read_b128 v[140:143], v153
	ds_read_b128 v[144:147], v153 offset:1024
	ds_read_b128 v[148:151], v153 offset:2048
	ds_read_b128 v[154:157], v153 offset:3072
	v_add_u32_e32 v153, s75, v138
	ds_read_b128 v[158:161], v153
	ds_read_b128 v[162:165], v153 offset:1024
	ds_read_b128 v[170:173], v153 offset:2048
	ds_read_b128 v[174:177], v153 offset:3072
	s_add_u32 s72, s0, 0x40000
	s_addc_u32 s73, s54, 0
	v_lshl_add_u64 v[166:167], s[72:73], 0, v[134:135]
	s_add_i32 m0, s79, 0xc000
	ds_read_b128 v[178:181], v139
	ds_read_b128 v[182:185], v139 offset:1024
	ds_read_b128 v[186:189], v139 offset:2048
	ds_read_b128 v[190:193], v139 offset:3072
	ds_read_b128 v[194:197], v139 offset:4096
	ds_read_b128 v[202:205], v139 offset:5120
	ds_read_b128 v[206:209], v139 offset:6144
	ds_read_b128 v[210:213], v139 offset:7168
	global_load_lds_dwordx4 v[166:167], off
	v_lshl_add_u64 v[166:167], s[72:73], 0, v[136:137]
	s_add_i32 m0, s79, 0xe000
	s_nop 0
	global_load_lds_dwordx4 v[166:167], off
	s_waitcnt vmcnt(8)
	s_waitcnt lgkmcnt(0)
	s_barrier
	s_waitcnt lgkmcnt(0)
	v_mfma_f32_16x16x32_bf16 v[130:133], v[140:143], v[178:181], v[130:133]
	v_mfma_f32_16x16x32_bf16 v[126:129], v[148:151], v[178:181], v[126:129]
	v_mfma_f32_16x16x32_bf16 v[122:125], v[140:143], v[186:189], v[122:125]
	v_mfma_f32_16x16x32_bf16 v[118:121], v[148:151], v[186:189], v[118:121]
	v_mfma_f32_16x16x32_bf16 v[114:117], v[140:143], v[194:197], v[114:117]
	v_mfma_f32_16x16x32_bf16 v[110:113], v[148:151], v[194:197], v[110:113]
	v_mfma_f32_16x16x32_bf16 v[106:109], v[140:143], v[206:209], v[106:109]
	v_mfma_f32_16x16x32_bf16 v[102:105], v[148:151], v[206:209], v[102:105]
	v_mfma_f32_16x16x32_bf16 v[130:133], v[144:147], v[182:185], v[130:133]
	v_mfma_f32_16x16x32_bf16 v[126:129], v[154:157], v[182:185], v[126:129]
	v_mfma_f32_16x16x32_bf16 v[122:125], v[144:147], v[190:193], v[122:125]
	v_mfma_f32_16x16x32_bf16 v[118:121], v[154:157], v[190:193], v[118:121]
	v_mfma_f32_16x16x32_bf16 v[114:117], v[144:147], v[202:205], v[114:117]
	v_mfma_f32_16x16x32_bf16 v[110:113], v[154:157], v[202:205], v[110:113]
	v_mfma_f32_16x16x32_bf16 v[106:109], v[144:147], v[210:213], v[106:109]
	v_mfma_f32_16x16x32_bf16 v[102:105], v[154:157], v[210:213], v[102:105]
	v_mfma_f32_16x16x32_bf16 v[90:93], v[158:161], v[178:181], v[90:93]
	v_mfma_f32_16x16x32_bf16 v[82:85], v[170:173], v[178:181], v[82:85]
	v_mfma_f32_16x16x32_bf16 v[74:77], v[158:161], v[186:189], v[74:77]
	v_mfma_f32_16x16x32_bf16 v[66:69], v[170:173], v[186:189], v[66:69]
	v_mfma_f32_16x16x32_bf16 v[58:61], v[158:161], v[194:197], v[58:61]
	v_mfma_f32_16x16x32_bf16 v[54:57], v[170:173], v[194:197], v[54:57]
	v_mfma_f32_16x16x32_bf16 v[42:45], v[158:161], v[206:209], v[42:45]
	v_mfma_f32_16x16x32_bf16 v[38:41], v[170:173], v[206:209], v[38:41]
	v_mfma_f32_16x16x32_bf16 v[90:93], v[162:165], v[182:185], v[90:93]
	v_mfma_f32_16x16x32_bf16 v[82:85], v[174:177], v[182:185], v[82:85]
	v_mfma_f32_16x16x32_bf16 v[74:77], v[162:165], v[190:193], v[74:77]
	v_mfma_f32_16x16x32_bf16 v[66:69], v[174:177], v[190:193], v[66:69]
	v_mfma_f32_16x16x32_bf16 v[58:61], v[162:165], v[202:205], v[58:61]
	v_mfma_f32_16x16x32_bf16 v[54:57], v[174:177], v[202:205], v[54:57]
	v_mfma_f32_16x16x32_bf16 v[42:45], v[162:165], v[210:213], v[42:45]
	v_mfma_f32_16x16x32_bf16 v[38:41], v[174:177], v[210:213], v[38:41]
	s_barrier
	s_add_i32 s0, s74, s78
	v_lshl_add_u64 v[166:167], s[34:35], 0, v[32:33]
	s_mov_b32 m0, s0
	ds_read_b128 v[178:181], v139 offset:16384
	ds_read_b128 v[182:185], v139 offset:17408
	ds_read_b128 v[186:189], v139 offset:18432
	ds_read_b128 v[190:193], v139 offset:19456
	ds_read_b128 v[194:197], v139 offset:20480
	ds_read_b128 v[202:205], v139 offset:21504
	ds_read_b128 v[206:209], v139 offset:22528
	ds_read_b128 v[210:213], v139 offset:23552
	global_load_lds_dwordx4 v[166:167], off
	s_add_i32 m0, s0, 0x2000
	s_add_u32 s72, s34, 0x40000
	v_lshl_add_u64 v[198:199], s[34:35], 0, v[34:35]
	s_addc_u32 s73, s35, 0
	s_add_i32 s0, s75, s78
	global_load_lds_dwordx4 v[198:199], off
	v_lshl_add_u64 v[214:215], s[72:73], 0, v[32:33]
	s_mov_b32 m0, s0
	v_lshl_add_u64 v[218:219], s[70:71], 0, v[136:137]
	global_load_lds_dwordx4 v[214:215], off
	v_lshl_add_u64 v[214:215], s[72:73], 0, v[34:35]
	s_add_i32 m0, s0, 0x2000
	s_nop 0
	global_load_lds_dwordx4 v[214:215], off
	v_lshl_add_u64 v[214:215], s[70:71], 0, v[134:135]
	s_mov_b32 m0, s79
	s_nop 0
	global_load_lds_dwordx4 v[214:215], off
	s_mov_b32 m0, s80
	s_nop 0
	global_load_lds_dwordx4 v[218:219], off
	s_waitcnt vmcnt(8)
	s_waitcnt lgkmcnt(0)
	s_barrier
	s_waitcnt lgkmcnt(0)
	v_mfma_f32_16x16x32_bf16 v[98:101], v[140:143], v[178:181], v[98:101]
	v_mfma_f32_16x16x32_bf16 v[94:97], v[148:151], v[178:181], v[94:97]
	v_mfma_f32_16x16x32_bf16 v[86:89], v[140:143], v[186:189], v[86:89]
	v_mfma_f32_16x16x32_bf16 v[78:81], v[148:151], v[186:189], v[78:81]
	v_mfma_f32_16x16x32_bf16 v[70:73], v[140:143], v[194:197], v[70:73]
	v_mfma_f32_16x16x32_bf16 v[62:65], v[148:151], v[194:197], v[62:65]
	v_mfma_f32_16x16x32_bf16 v[50:53], v[140:143], v[206:209], v[50:53]
	v_mfma_f32_16x16x32_bf16 v[46:49], v[148:151], v[206:209], v[46:49]
	v_mfma_f32_16x16x32_bf16 v[98:101], v[144:147], v[182:185], v[98:101]
	v_mfma_f32_16x16x32_bf16 v[94:97], v[154:157], v[182:185], v[94:97]
	v_mfma_f32_16x16x32_bf16 v[86:89], v[144:147], v[190:193], v[86:89]
	v_mfma_f32_16x16x32_bf16 v[78:81], v[154:157], v[190:193], v[78:81]
	v_mfma_f32_16x16x32_bf16 v[70:73], v[144:147], v[202:205], v[70:73]
	v_mfma_f32_16x16x32_bf16 v[62:65], v[154:157], v[202:205], v[62:65]
	v_mfma_f32_16x16x32_bf16 v[50:53], v[144:147], v[210:213], v[50:53]
	v_mfma_f32_16x16x32_bf16 v[46:49], v[154:157], v[210:213], v[46:49]
	v_mfma_f32_16x16x32_bf16 v[28:31], v[158:161], v[178:181], v[28:31]
	v_mfma_f32_16x16x32_bf16 v[24:27], v[170:173], v[178:181], v[24:27]
	v_mfma_f32_16x16x32_bf16 v[20:23], v[158:161], v[186:189], v[20:23]
	v_mfma_f32_16x16x32_bf16 v[16:19], v[170:173], v[186:189], v[16:19]
	v_mfma_f32_16x16x32_bf16 v[12:15], v[158:161], v[194:197], v[12:15]
	v_mfma_f32_16x16x32_bf16 v[8:11], v[170:173], v[194:197], v[8:11]
	v_mfma_f32_16x16x32_bf16 v[4:7], v[158:161], v[206:209], v[4:7]
	v_mfma_f32_16x16x32_bf16 v[0:3], v[170:173], v[206:209], v[0:3]
	v_mfma_f32_16x16x32_bf16 v[28:31], v[162:165], v[182:185], v[28:31]
	v_mfma_f32_16x16x32_bf16 v[24:27], v[174:177], v[182:185], v[24:27]
	v_mfma_f32_16x16x32_bf16 v[20:23], v[162:165], v[190:193], v[20:23]
	v_mfma_f32_16x16x32_bf16 v[16:19], v[174:177], v[190:193], v[16:19]
	v_mfma_f32_16x16x32_bf16 v[12:15], v[162:165], v[202:205], v[12:15]
	v_mfma_f32_16x16x32_bf16 v[8:11], v[174:177], v[202:205], v[8:11]
	v_mfma_f32_16x16x32_bf16 v[4:7], v[162:165], v[210:213], v[4:7]
	v_mfma_f32_16x16x32_bf16 v[0:3], v[174:177], v[210:213], v[0:3]
	s_barrier
	s_add_i32 s0, 0, 0x18000
	v_add_u32_e32 v153, s0, v138
	s_add_i32 s54, 0, 0x1c000
	ds_read_b128 v[140:143], v153
	ds_read_b128 v[144:147], v153 offset:1024
	ds_read_b128 v[148:151], v153 offset:2048
	ds_read_b128 v[154:157], v153 offset:3072
	v_add_u32_e32 v153, s54, v138
	ds_read_b128 v[158:161], v153
	ds_read_b128 v[162:165], v153 offset:1024
	ds_read_b128 v[170:173], v153 offset:2048
	ds_read_b128 v[174:177], v153 offset:3072
	s_add_u32 s70, s70, 0x40000
	s_addc_u32 s71, s71, 0
	s_mov_b32 m0, s81
	v_lshl_add_u64 v[220:221], s[70:71], 0, v[134:135]
	ds_read_b128 v[178:181], v139 offset:32768
	ds_read_b128 v[182:185], v139 offset:33792
	ds_read_b128 v[186:189], v139 offset:34816
	ds_read_b128 v[190:193], v139 offset:35840
	ds_read_b128 v[194:197], v139 offset:36864
	ds_read_b128 v[202:205], v139 offset:37888
	ds_read_b128 v[206:209], v139 offset:38912
	ds_read_b128 v[210:213], v139 offset:39936
	global_load_lds_dwordx4 v[220:221], off
	v_lshl_add_u64 v[220:221], s[70:71], 0, v[136:137]
	s_mov_b32 m0, s82
	s_nop 0
	global_load_lds_dwordx4 v[220:221], off
	s_waitcnt vmcnt(8)
	s_waitcnt lgkmcnt(0)
	s_barrier
	s_waitcnt lgkmcnt(0)
	v_mfma_f32_16x16x32_bf16 v[130:133], v[140:143], v[178:181], v[130:133]
	v_mfma_f32_16x16x32_bf16 v[126:129], v[148:151], v[178:181], v[126:129]
	v_mfma_f32_16x16x32_bf16 v[122:125], v[140:143], v[186:189], v[122:125]
	v_mfma_f32_16x16x32_bf16 v[118:121], v[148:151], v[186:189], v[118:121]
	v_mfma_f32_16x16x32_bf16 v[114:117], v[140:143], v[194:197], v[114:117]
	v_mfma_f32_16x16x32_bf16 v[110:113], v[148:151], v[194:197], v[110:113]
	v_mfma_f32_16x16x32_bf16 v[106:109], v[140:143], v[206:209], v[106:109]
	v_mfma_f32_16x16x32_bf16 v[102:105], v[148:151], v[206:209], v[102:105]
	v_mfma_f32_16x16x32_bf16 v[130:133], v[144:147], v[182:185], v[130:133]
	v_mfma_f32_16x16x32_bf16 v[126:129], v[154:157], v[182:185], v[126:129]
	v_mfma_f32_16x16x32_bf16 v[122:125], v[144:147], v[190:193], v[122:125]
	v_mfma_f32_16x16x32_bf16 v[118:121], v[154:157], v[190:193], v[118:121]
	v_mfma_f32_16x16x32_bf16 v[114:117], v[144:147], v[202:205], v[114:117]
	v_mfma_f32_16x16x32_bf16 v[110:113], v[154:157], v[202:205], v[110:113]
	v_mfma_f32_16x16x32_bf16 v[106:109], v[144:147], v[210:213], v[106:109]
	v_mfma_f32_16x16x32_bf16 v[102:105], v[154:157], v[210:213], v[102:105]
	v_mfma_f32_16x16x32_bf16 v[90:93], v[158:161], v[178:181], v[90:93]
	v_mfma_f32_16x16x32_bf16 v[82:85], v[170:173], v[178:181], v[82:85]
	v_mfma_f32_16x16x32_bf16 v[74:77], v[158:161], v[186:189], v[74:77]
	v_mfma_f32_16x16x32_bf16 v[66:69], v[170:173], v[186:189], v[66:69]
	v_mfma_f32_16x16x32_bf16 v[58:61], v[158:161], v[194:197], v[58:61]
	v_mfma_f32_16x16x32_bf16 v[54:57], v[170:173], v[194:197], v[54:57]
	v_mfma_f32_16x16x32_bf16 v[42:45], v[158:161], v[206:209], v[42:45]
	v_mfma_f32_16x16x32_bf16 v[38:41], v[170:173], v[206:209], v[38:41]
	v_mfma_f32_16x16x32_bf16 v[90:93], v[162:165], v[182:185], v[90:93]
	v_mfma_f32_16x16x32_bf16 v[82:85], v[174:177], v[182:185], v[82:85]
	v_mfma_f32_16x16x32_bf16 v[74:77], v[162:165], v[190:193], v[74:77]
	v_mfma_f32_16x16x32_bf16 v[66:69], v[174:177], v[190:193], v[66:69]
	v_mfma_f32_16x16x32_bf16 v[58:61], v[162:165], v[202:205], v[58:61]
	v_mfma_f32_16x16x32_bf16 v[54:57], v[174:177], v[202:205], v[54:57]
	v_mfma_f32_16x16x32_bf16 v[42:45], v[162:165], v[210:213], v[42:45]
	v_mfma_f32_16x16x32_bf16 v[38:41], v[174:177], v[210:213], v[38:41]
	s_barrier
	s_add_i32 s0, s0, s78
	v_lshl_add_u64 v[166:167], v[166:167], 0, s[68:69]
	s_mov_b32 m0, s0
	ds_read_b128 v[178:181], v139 offset:49152
	ds_read_b128 v[182:185], v139 offset:50176
	ds_read_b128 v[186:189], v139 offset:51200
	ds_read_b128 v[190:193], v139 offset:52224
	ds_read_b128 v[194:197], v139 offset:53248
	ds_read_b128 v[202:205], v139 offset:54272
	ds_read_b128 v[206:209], v139 offset:55296
	ds_read_b128 v[210:213], v139 offset:56320
	global_load_lds_dwordx4 v[166:167], off
	s_add_i32 m0, s0, 0x2000
	s_add_u32 s34, s34, 0x40080
	v_lshl_add_u64 v[166:167], v[198:199], 0, s[68:69]
	s_addc_u32 s35, s35, 0
	s_add_i32 s0, s54, s78
	global_load_lds_dwordx4 v[166:167], off
	v_lshl_add_u64 v[166:167], s[34:35], 0, v[32:33]
	s_mov_b32 m0, s0
	s_nop 0
	global_load_lds_dwordx4 v[166:167], off
	v_lshl_add_u64 v[166:167], s[34:35], 0, v[34:35]
	s_add_i32 m0, s0, 0x2000
	s_nop 0
	global_load_lds_dwordx4 v[166:167], off
	v_lshl_add_u64 v[166:167], v[214:215], 0, s[68:69]
	s_mov_b32 m0, s83
	s_nop 0
	global_load_lds_dwordx4 v[166:167], off
	v_lshl_add_u64 v[166:167], v[218:219], 0, s[68:69]
	s_mov_b32 m0, s86
	s_nop 0
	global_load_lds_dwordx4 v[166:167], off
	s_waitcnt vmcnt(8)
	s_waitcnt lgkmcnt(0)
	s_barrier
	s_waitcnt lgkmcnt(0)
	v_mfma_f32_16x16x32_bf16 v[98:101], v[140:143], v[178:181], v[98:101]
	v_mfma_f32_16x16x32_bf16 v[94:97], v[148:151], v[178:181], v[94:97]
	v_mfma_f32_16x16x32_bf16 v[86:89], v[140:143], v[186:189], v[86:89]
	v_mfma_f32_16x16x32_bf16 v[78:81], v[148:151], v[186:189], v[78:81]
	v_mfma_f32_16x16x32_bf16 v[70:73], v[140:143], v[194:197], v[70:73]
	v_mfma_f32_16x16x32_bf16 v[62:65], v[148:151], v[194:197], v[62:65]
	v_mfma_f32_16x16x32_bf16 v[50:53], v[140:143], v[206:209], v[50:53]
	v_mfma_f32_16x16x32_bf16 v[46:49], v[148:151], v[206:209], v[46:49]
	v_mfma_f32_16x16x32_bf16 v[98:101], v[144:147], v[182:185], v[98:101]
	v_mfma_f32_16x16x32_bf16 v[94:97], v[154:157], v[182:185], v[94:97]
	v_mfma_f32_16x16x32_bf16 v[86:89], v[144:147], v[190:193], v[86:89]
	v_mfma_f32_16x16x32_bf16 v[78:81], v[154:157], v[190:193], v[78:81]
	v_mfma_f32_16x16x32_bf16 v[70:73], v[144:147], v[202:205], v[70:73]
	v_mfma_f32_16x16x32_bf16 v[62:65], v[154:157], v[202:205], v[62:65]
	v_mfma_f32_16x16x32_bf16 v[50:53], v[144:147], v[210:213], v[50:53]
	v_mfma_f32_16x16x32_bf16 v[46:49], v[154:157], v[210:213], v[46:49]
	v_mfma_f32_16x16x32_bf16 v[28:31], v[158:161], v[178:181], v[28:31]
	v_mfma_f32_16x16x32_bf16 v[24:27], v[170:173], v[178:181], v[24:27]
	v_mfma_f32_16x16x32_bf16 v[20:23], v[158:161], v[186:189], v[20:23]
	v_mfma_f32_16x16x32_bf16 v[16:19], v[170:173], v[186:189], v[16:19]
	v_mfma_f32_16x16x32_bf16 v[12:15], v[158:161], v[194:197], v[12:15]
	v_mfma_f32_16x16x32_bf16 v[8:11], v[170:173], v[194:197], v[8:11]
	v_mfma_f32_16x16x32_bf16 v[4:7], v[158:161], v[206:209], v[4:7]
	v_mfma_f32_16x16x32_bf16 v[0:3], v[170:173], v[206:209], v[0:3]
	v_mfma_f32_16x16x32_bf16 v[28:31], v[162:165], v[182:185], v[28:31]
	v_mfma_f32_16x16x32_bf16 v[24:27], v[174:177], v[182:185], v[24:27]
	v_mfma_f32_16x16x32_bf16 v[20:23], v[162:165], v[190:193], v[20:23]
	v_mfma_f32_16x16x32_bf16 v[16:19], v[174:177], v[190:193], v[16:19]
	v_mfma_f32_16x16x32_bf16 v[12:15], v[162:165], v[202:205], v[12:15]
	v_mfma_f32_16x16x32_bf16 v[8:11], v[174:177], v[202:205], v[8:11]
	v_mfma_f32_16x16x32_bf16 v[4:7], v[162:165], v[210:213], v[4:7]
	v_mfma_f32_16x16x32_bf16 v[0:3], v[174:177], v[210:213], v[0:3]
	s_barrier
	s_cmp_gt_u32 s55, 13
	s_cbranch_scc1 .LBB0_1633
	s_mov_b32 s55, s92
	s_branch .LBB0_1598

.LBB0_1741:
.LBB0_1742:
	s_or_b32 s92, s90, 1
	s_lshl_b64 s[54:55], s[92:93], 7
	s_add_u32 s0, s8, s54
	s_addc_u32 s70, s9, s55
	s_add_i32 s92, s90, 2
	s_lshl_b64 s[54:55], s[92:93], 7
	s_add_u32 s71, s8, s54
	s_addc_u32 s72, s9, s55
	s_and_b64 s[64:65], s[34:35], exec
	s_cselect_b32 s65, s11, s72
	s_cselect_b32 s64, s87, s71
	s_add_u32 s54, s6, s54
	s_addc_u32 s55, s7, s55
	s_and_b64 s[34:35], s[34:35], exec
	s_cselect_b32 s35, s17, s55
	s_cselect_b32 s34, s88, s54
	s_add_i32 s71, 0, 0x10000
	s_add_i32 s72, 0, 0x14000
	v_add_u32_e32 v152, s71, v138
	v_add_u32_e32 v157, s72, v138
	ds_read_b128 v[140:143], v152
	ds_read_b128 v[144:147], v152 offset:1024
	ds_read_b128 v[148:151], v152 offset:2048
	ds_read_b128 v[152:155], v152 offset:3072
	ds_read_b128 v[158:161], v157
	ds_read_b128 v[162:165], v157 offset:1024
	ds_read_b128 v[166:169], v157 offset:2048
	ds_read_b128 v[172:175], v157 offset:3072
	s_add_u32 s54, s0, 0x40000
	s_addc_u32 s55, s70, 0
	v_lshl_add_u64 v[210:211], s[54:55], 0, v[134:135]
	s_add_i32 m0, s77, 0xc000
	ds_read_b128 v[176:179], v139
	ds_read_b128 v[180:183], v139 offset:1024
	ds_read_b128 v[184:187], v139 offset:2048
	ds_read_b128 v[188:191], v139 offset:3072
	ds_read_b128 v[192:195], v139 offset:4096
	ds_read_b128 v[196:199], v139 offset:5120
	ds_read_b128 v[202:205], v139 offset:6144
	ds_read_b128 v[206:209], v139 offset:7168
	global_load_lds_dwordx4 v[210:211], off
	v_lshl_add_u64 v[210:211], s[54:55], 0, v[136:137]
	s_add_i32 m0, s77, 0xe000
	s_nop 0
	global_load_lds_dwordx4 v[210:211], off
	s_waitcnt vmcnt(8)
	s_waitcnt lgkmcnt(0)
	s_barrier
	s_waitcnt lgkmcnt(0)
	v_mfma_f32_16x16x32_bf16 v[130:133], v[140:143], v[176:179], v[130:133]
	v_mfma_f32_16x16x32_bf16 v[126:129], v[148:151], v[176:179], v[126:129]
	v_mfma_f32_16x16x32_bf16 v[122:125], v[140:143], v[184:187], v[122:125]
	v_mfma_f32_16x16x32_bf16 v[118:121], v[148:151], v[184:187], v[118:121]
	v_mfma_f32_16x16x32_bf16 v[114:117], v[140:143], v[192:195], v[114:117]
	v_mfma_f32_16x16x32_bf16 v[110:113], v[148:151], v[192:195], v[110:113]
	v_mfma_f32_16x16x32_bf16 v[106:109], v[140:143], v[202:205], v[106:109]
	v_mfma_f32_16x16x32_bf16 v[102:105], v[148:151], v[202:205], v[102:105]
	v_mfma_f32_16x16x32_bf16 v[130:133], v[144:147], v[180:183], v[130:133]
	v_mfma_f32_16x16x32_bf16 v[126:129], v[152:155], v[180:183], v[126:129]
	v_mfma_f32_16x16x32_bf16 v[122:125], v[144:147], v[188:191], v[122:125]
	v_mfma_f32_16x16x32_bf16 v[118:121], v[152:155], v[188:191], v[118:121]
	v_mfma_f32_16x16x32_bf16 v[114:117], v[144:147], v[196:199], v[114:117]
	v_mfma_f32_16x16x32_bf16 v[110:113], v[152:155], v[196:199], v[110:113]
	v_mfma_f32_16x16x32_bf16 v[106:109], v[144:147], v[206:209], v[106:109]
	v_mfma_f32_16x16x32_bf16 v[102:105], v[152:155], v[206:209], v[102:105]
	v_mfma_f32_16x16x32_bf16 v[90:93], v[158:161], v[176:179], v[90:93]
	v_mfma_f32_16x16x32_bf16 v[86:89], v[166:169], v[176:179], v[86:89]
	v_mfma_f32_16x16x32_bf16 v[78:81], v[158:161], v[184:187], v[78:81]
	v_mfma_f32_16x16x32_bf16 v[70:73], v[166:169], v[184:187], v[70:73]
	v_mfma_f32_16x16x32_bf16 v[62:65], v[158:161], v[192:195], v[62:65]
	v_mfma_f32_16x16x32_bf16 v[54:57], v[166:169], v[192:195], v[54:57]
	v_mfma_f32_16x16x32_bf16 v[50:53], v[158:161], v[202:205], v[50:53]
	v_mfma_f32_16x16x32_bf16 v[42:45], v[166:169], v[202:205], v[42:45]
	v_mfma_f32_16x16x32_bf16 v[90:93], v[162:165], v[180:183], v[90:93]
	v_mfma_f32_16x16x32_bf16 v[86:89], v[172:175], v[180:183], v[86:89]
	v_mfma_f32_16x16x32_bf16 v[78:81], v[162:165], v[188:191], v[78:81]
	v_mfma_f32_16x16x32_bf16 v[70:73], v[172:175], v[188:191], v[70:73]
	v_mfma_f32_16x16x32_bf16 v[62:65], v[162:165], v[196:199], v[62:65]
	v_mfma_f32_16x16x32_bf16 v[54:57], v[172:175], v[196:199], v[54:57]
	v_mfma_f32_16x16x32_bf16 v[50:53], v[162:165], v[206:209], v[50:53]
	v_mfma_f32_16x16x32_bf16 v[42:45], v[172:175], v[206:209], v[42:45]
	s_barrier
	s_add_i32 s0, s71, s47
	v_lshl_add_u64 v[210:211], s[34:35], 0, v[32:33]
	s_mov_b32 m0, s0
	ds_read_b128 v[176:179], v139 offset:16384
	ds_read_b128 v[180:183], v139 offset:17408
	ds_read_b128 v[184:187], v139 offset:18432
	ds_read_b128 v[188:191], v139 offset:19456
	ds_read_b128 v[192:195], v139 offset:20480
	ds_read_b128 v[196:199], v139 offset:21504
	ds_read_b128 v[202:205], v139 offset:22528
	ds_read_b128 v[206:209], v139 offset:23552
	global_load_lds_dwordx4 v[210:211], off
	s_add_i32 m0, s0, 0x2000
	s_add_u32 s54, s34, 0x40000
	v_lshl_add_u64 v[212:213], s[34:35], 0, v[34:35]
	s_addc_u32 s55, s35, 0
	s_add_i32 s0, s72, s47
	global_load_lds_dwordx4 v[212:213], off
	v_lshl_add_u64 v[214:215], s[54:55], 0, v[32:33]
	s_mov_b32 m0, s0
	v_lshl_add_u64 v[218:219], s[64:65], 0, v[136:137]
	global_load_lds_dwordx4 v[214:215], off
	v_lshl_add_u64 v[214:215], s[54:55], 0, v[34:35]
	s_add_i32 m0, s0, 0x2000
	s_nop 0
	global_load_lds_dwordx4 v[214:215], off
	v_lshl_add_u64 v[214:215], s[64:65], 0, v[134:135]
	s_mov_b32 m0, s77
	s_nop 0
	global_load_lds_dwordx4 v[214:215], off
	s_mov_b32 m0, s78
	s_nop 0
	global_load_lds_dwordx4 v[218:219], off
	s_waitcnt vmcnt(8)
	s_waitcnt lgkmcnt(0)
	s_barrier
	s_waitcnt lgkmcnt(0)
	v_mfma_f32_16x16x32_bf16 v[98:101], v[140:143], v[176:179], v[98:101]
	v_mfma_f32_16x16x32_bf16 v[94:97], v[148:151], v[176:179], v[94:97]
	v_mfma_f32_16x16x32_bf16 v[82:85], v[140:143], v[184:187], v[82:85]
	v_mfma_f32_16x16x32_bf16 v[74:77], v[148:151], v[184:187], v[74:77]
	v_mfma_f32_16x16x32_bf16 v[66:69], v[140:143], v[192:195], v[66:69]
	v_mfma_f32_16x16x32_bf16 v[58:61], v[148:151], v[192:195], v[58:61]
	v_mfma_f32_16x16x32_bf16 v[46:49], v[140:143], v[202:205], v[46:49]
	v_mfma_f32_16x16x32_bf16 v[38:41], v[148:151], v[202:205], v[38:41]
	v_mfma_f32_16x16x32_bf16 v[98:101], v[144:147], v[180:183], v[98:101]
	v_mfma_f32_16x16x32_bf16 v[94:97], v[152:155], v[180:183], v[94:97]
	v_mfma_f32_16x16x32_bf16 v[82:85], v[144:147], v[188:191], v[82:85]
	v_mfma_f32_16x16x32_bf16 v[74:77], v[152:155], v[188:191], v[74:77]
	v_mfma_f32_16x16x32_bf16 v[66:69], v[144:147], v[196:199], v[66:69]
	v_mfma_f32_16x16x32_bf16 v[58:61], v[152:155], v[196:199], v[58:61]
	v_mfma_f32_16x16x32_bf16 v[46:49], v[144:147], v[206:209], v[46:49]
	v_mfma_f32_16x16x32_bf16 v[38:41], v[152:155], v[206:209], v[38:41]
	v_mfma_f32_16x16x32_bf16 v[28:31], v[158:161], v[176:179], v[28:31]
	v_mfma_f32_16x16x32_bf16 v[24:27], v[166:169], v[176:179], v[24:27]
	v_mfma_f32_16x16x32_bf16 v[20:23], v[158:161], v[184:187], v[20:23]
	v_mfma_f32_16x16x32_bf16 v[16:19], v[166:169], v[184:187], v[16:19]
	v_mfma_f32_16x16x32_bf16 v[12:15], v[158:161], v[192:195], v[12:15]
	v_mfma_f32_16x16x32_bf16 v[8:11], v[166:169], v[192:195], v[8:11]
	v_mfma_f32_16x16x32_bf16 v[4:7], v[158:161], v[202:205], v[4:7]
	v_mfma_f32_16x16x32_bf16 v[0:3], v[166:169], v[202:205], v[0:3]
	v_mfma_f32_16x16x32_bf16 v[28:31], v[162:165], v[180:183], v[28:31]
	v_mfma_f32_16x16x32_bf16 v[24:27], v[172:175], v[180:183], v[24:27]
	v_mfma_f32_16x16x32_bf16 v[20:23], v[162:165], v[188:191], v[20:23]
	v_mfma_f32_16x16x32_bf16 v[16:19], v[172:175], v[188:191], v[16:19]
	v_mfma_f32_16x16x32_bf16 v[12:15], v[162:165], v[196:199], v[12:15]
	v_mfma_f32_16x16x32_bf16 v[8:11], v[172:175], v[196:199], v[8:11]
	v_mfma_f32_16x16x32_bf16 v[4:7], v[162:165], v[206:209], v[4:7]
	v_mfma_f32_16x16x32_bf16 v[0:3], v[172:175], v[206:209], v[0:3]
	s_barrier
	s_add_i32 s0, 0, 0x18000
	s_add_i32 s70, 0, 0x1c000
	v_add_u32_e32 v152, s0, v138
	v_add_u32_e32 v157, s70, v138
	ds_read_b128 v[140:143], v152
	ds_read_b128 v[144:147], v152 offset:1024
	ds_read_b128 v[148:151], v152 offset:2048
	ds_read_b128 v[152:155], v152 offset:3072
	ds_read_b128 v[158:161], v157
	ds_read_b128 v[162:165], v157 offset:1024
	ds_read_b128 v[166:169], v157 offset:2048
	ds_read_b128 v[172:175], v157 offset:3072
	s_add_u32 s54, s64, 0x40000
	s_addc_u32 s55, s65, 0
	s_mov_b32 m0, s79
	v_lshl_add_u64 v[220:221], s[54:55], 0, v[134:135]
	ds_read_b128 v[176:179], v139 offset:32768
	ds_read_b128 v[180:183], v139 offset:33792
	ds_read_b128 v[184:187], v139 offset:34816
	ds_read_b128 v[188:191], v139 offset:35840
	ds_read_b128 v[192:195], v139 offset:36864
	ds_read_b128 v[196:199], v139 offset:37888
	ds_read_b128 v[202:205], v139 offset:38912
	ds_read_b128 v[206:209], v139 offset:39936
	global_load_lds_dwordx4 v[220:221], off
	v_lshl_add_u64 v[220:221], s[54:55], 0, v[136:137]
	s_mov_b32 m0, s80
	s_nop 0
	global_load_lds_dwordx4 v[220:221], off
	s_waitcnt vmcnt(8)
	s_waitcnt lgkmcnt(0)
	s_barrier
	s_waitcnt lgkmcnt(0)
	v_mfma_f32_16x16x32_bf16 v[130:133], v[140:143], v[176:179], v[130:133]
	v_mfma_f32_16x16x32_bf16 v[126:129], v[148:151], v[176:179], v[126:129]
	v_mfma_f32_16x16x32_bf16 v[122:125], v[140:143], v[184:187], v[122:125]
	v_mfma_f32_16x16x32_bf16 v[118:121], v[148:151], v[184:187], v[118:121]
	v_mfma_f32_16x16x32_bf16 v[114:117], v[140:143], v[192:195], v[114:117]
	v_mfma_f32_16x16x32_bf16 v[110:113], v[148:151], v[192:195], v[110:113]
	v_mfma_f32_16x16x32_bf16 v[106:109], v[140:143], v[202:205], v[106:109]
	v_mfma_f32_16x16x32_bf16 v[102:105], v[148:151], v[202:205], v[102:105]
	v_mfma_f32_16x16x32_bf16 v[130:133], v[144:147], v[180:183], v[130:133]
	v_mfma_f32_16x16x32_bf16 v[126:129], v[152:155], v[180:183], v[126:129]
	v_mfma_f32_16x16x32_bf16 v[122:125], v[144:147], v[188:191], v[122:125]
	v_mfma_f32_16x16x32_bf16 v[118:121], v[152:155], v[188:191], v[118:121]
	v_mfma_f32_16x16x32_bf16 v[114:117], v[144:147], v[196:199], v[114:117]
	v_mfma_f32_16x16x32_bf16 v[110:113], v[152:155], v[196:199], v[110:113]
	v_mfma_f32_16x16x32_bf16 v[106:109], v[144:147], v[206:209], v[106:109]
	v_mfma_f32_16x16x32_bf16 v[102:105], v[152:155], v[206:209], v[102:105]
	v_mfma_f32_16x16x32_bf16 v[90:93], v[158:161], v[176:179], v[90:93]
	v_mfma_f32_16x16x32_bf16 v[86:89], v[166:169], v[176:179], v[86:89]
	v_mfma_f32_16x16x32_bf16 v[78:81], v[158:161], v[184:187], v[78:81]
	v_mfma_f32_16x16x32_bf16 v[70:73], v[166:169], v[184:187], v[70:73]
	v_mfma_f32_16x16x32_bf16 v[62:65], v[158:161], v[192:195], v[62:65]
	v_mfma_f32_16x16x32_bf16 v[54:57], v[166:169], v[192:195], v[54:57]
	v_mfma_f32_16x16x32_bf16 v[50:53], v[158:161], v[202:205], v[50:53]
	v_mfma_f32_16x16x32_bf16 v[42:45], v[166:169], v[202:205], v[42:45]
	v_mfma_f32_16x16x32_bf16 v[90:93], v[162:165], v[180:183], v[90:93]
	v_mfma_f32_16x16x32_bf16 v[86:89], v[172:175], v[180:183], v[86:89]
	v_mfma_f32_16x16x32_bf16 v[78:81], v[162:165], v[188:191], v[78:81]
	v_mfma_f32_16x16x32_bf16 v[70:73], v[172:175], v[188:191], v[70:73]
	v_mfma_f32_16x16x32_bf16 v[62:65], v[162:165], v[196:199], v[62:65]
	v_mfma_f32_16x16x32_bf16 v[54:57], v[172:175], v[196:199], v[54:57]
	v_mfma_f32_16x16x32_bf16 v[50:53], v[162:165], v[206:209], v[50:53]
	v_mfma_f32_16x16x32_bf16 v[42:45], v[172:175], v[206:209], v[42:45]
	s_barrier
	s_add_i32 s0, s0, s47
	v_lshl_add_u64 v[210:211], v[210:211], 0, s[68:69]
	s_mov_b32 m0, s0
	ds_read_b128 v[176:179], v139 offset:49152
	ds_read_b128 v[180:183], v139 offset:50176
	ds_read_b128 v[184:187], v139 offset:51200
	ds_read_b128 v[188:191], v139 offset:52224
	ds_read_b128 v[192:195], v139 offset:53248
	ds_read_b128 v[196:199], v139 offset:54272
	ds_read_b128 v[202:205], v139 offset:55296
	ds_read_b128 v[206:209], v139 offset:56320
	global_load_lds_dwordx4 v[210:211], off
	s_add_i32 m0, s0, 0x2000
	s_add_u32 s34, s34, 0x40080
	v_lshl_add_u64 v[210:211], v[212:213], 0, s[68:69]
	s_addc_u32 s35, s35, 0
	s_add_i32 s0, s70, s47
	global_load_lds_dwordx4 v[210:211], off
	v_lshl_add_u64 v[210:211], s[34:35], 0, v[32:33]
	s_mov_b32 m0, s0
	s_nop 0
	global_load_lds_dwordx4 v[210:211], off
	v_lshl_add_u64 v[210:211], s[34:35], 0, v[34:35]
	s_add_i32 m0, s0, 0x2000
	s_nop 0
	global_load_lds_dwordx4 v[210:211], off
	v_lshl_add_u64 v[210:211], v[214:215], 0, s[68:69]
	s_mov_b32 m0, s81
	s_nop 0
	global_load_lds_dwordx4 v[210:211], off
	v_lshl_add_u64 v[210:211], v[218:219], 0, s[68:69]
	s_mov_b32 m0, s82
	s_nop 0
	global_load_lds_dwordx4 v[210:211], off
	s_waitcnt vmcnt(8)
	s_waitcnt lgkmcnt(0)
	s_barrier
	s_waitcnt lgkmcnt(0)
	v_mfma_f32_16x16x32_bf16 v[98:101], v[140:143], v[176:179], v[98:101]
	v_mfma_f32_16x16x32_bf16 v[94:97], v[148:151], v[176:179], v[94:97]
	v_mfma_f32_16x16x32_bf16 v[82:85], v[140:143], v[184:187], v[82:85]
	v_mfma_f32_16x16x32_bf16 v[74:77], v[148:151], v[184:187], v[74:77]
	v_mfma_f32_16x16x32_bf16 v[66:69], v[140:143], v[192:195], v[66:69]
	v_mfma_f32_16x16x32_bf16 v[58:61], v[148:151], v[192:195], v[58:61]
	v_mfma_f32_16x16x32_bf16 v[46:49], v[140:143], v[202:205], v[46:49]
	v_mfma_f32_16x16x32_bf16 v[38:41], v[148:151], v[202:205], v[38:41]
	v_mfma_f32_16x16x32_bf16 v[98:101], v[144:147], v[180:183], v[98:101]
	v_mfma_f32_16x16x32_bf16 v[94:97], v[152:155], v[180:183], v[94:97]
	v_mfma_f32_16x16x32_bf16 v[82:85], v[144:147], v[188:191], v[82:85]
	v_mfma_f32_16x16x32_bf16 v[74:77], v[152:155], v[188:191], v[74:77]
	v_mfma_f32_16x16x32_bf16 v[66:69], v[144:147], v[196:199], v[66:69]
	v_mfma_f32_16x16x32_bf16 v[58:61], v[152:155], v[196:199], v[58:61]
	v_mfma_f32_16x16x32_bf16 v[46:49], v[144:147], v[206:209], v[46:49]
	v_mfma_f32_16x16x32_bf16 v[38:41], v[152:155], v[206:209], v[38:41]
	v_mfma_f32_16x16x32_bf16 v[28:31], v[158:161], v[176:179], v[28:31]
	v_mfma_f32_16x16x32_bf16 v[24:27], v[166:169], v[176:179], v[24:27]
	v_mfma_f32_16x16x32_bf16 v[20:23], v[158:161], v[184:187], v[20:23]
	v_mfma_f32_16x16x32_bf16 v[16:19], v[166:169], v[184:187], v[16:19]
	v_mfma_f32_16x16x32_bf16 v[12:15], v[158:161], v[192:195], v[12:15]
	v_mfma_f32_16x16x32_bf16 v[8:11], v[166:169], v[192:195], v[8:11]
	v_mfma_f32_16x16x32_bf16 v[4:7], v[158:161], v[202:205], v[4:7]
	v_mfma_f32_16x16x32_bf16 v[0:3], v[166:169], v[202:205], v[0:3]
	v_mfma_f32_16x16x32_bf16 v[28:31], v[162:165], v[180:183], v[28:31]
	v_mfma_f32_16x16x32_bf16 v[24:27], v[172:175], v[180:183], v[24:27]
	v_mfma_f32_16x16x32_bf16 v[20:23], v[162:165], v[188:191], v[20:23]
	v_mfma_f32_16x16x32_bf16 v[16:19], v[172:175], v[188:191], v[16:19]
	v_mfma_f32_16x16x32_bf16 v[12:15], v[162:165], v[196:199], v[12:15]
	v_mfma_f32_16x16x32_bf16 v[8:11], v[172:175], v[196:199], v[8:11]
	v_mfma_f32_16x16x32_bf16 v[4:7], v[162:165], v[206:209], v[4:7]
	v_mfma_f32_16x16x32_bf16 v[0:3], v[172:175], v[206:209], v[0:3]
	s_barrier
	s_cmp_gt_u32 s90, 13
	s_cbranch_scc1 .LBB0_1744
	s_mov_b32 s90, s92
	s_branch .LBB0_1709
